# x3 + removed the per-block s_setprio 1/0 flips around the GEMM K-loop MFMA blocks (age-based arbitration between the loading and computing wave)
# speedup vs baseline: 1.0115x; 1.0011x over previous
.LBB0_541:
	s_add_u32 s6, s4, 0xfffc0080
	s_addc_u32 s7, s5, -1
	s_add_i32 s61, 0, 0x10000
	s_cmp_eq_u32 s17, 12
	s_cselect_b32 s9, s11, s7
	s_cselect_b32 s8, s12, s6
	v_add_u32_e32 v2, s61, v167
	s_cselect_b32 s7, s13, s16
	s_cselect_b32 s6, s14, s15
	s_add_i32 s77, 0, 0x14000
	ds_read_b128 v[132:135], v2
	ds_read_b128 v[148:151], v2 offset:1024
	ds_read_b128 v[152:155], v2 offset:2048
	ds_read_b128 v[156:159], v2 offset:3072
	v_add_u32_e32 v2, s77, v167
	ds_read_b128 v[160:163], v2
	ds_read_b128 v[170:173], v2 offset:1024
	ds_read_b128 v[174:177], v2 offset:2048
	ds_read_b128 v[178:181], v2 offset:3072
	v_lshl_add_u64 v[164:165], s[4:5], 0, v[144:145]
	s_add_i32 m0, s84, 0xc000
	ds_read_b128 v[182:185], v168
	ds_read_b128 v[186:189], v168 offset:1024
	ds_read_b128 v[190:193], v168 offset:2048
	ds_read_b128 v[194:197], v168 offset:3072
	ds_read_b128 v[198:201], v168 offset:4096
	ds_read_b128 v[202:205], v168 offset:5120
	ds_read_b128 v[218:221], v168 offset:6144
	ds_read_b128 v[222:225], v168 offset:7168
	global_load_lds_dwordx4 v[164:165], off
	v_lshl_add_u64 v[164:165], s[4:5], 0, v[146:147]
	s_add_i32 m0, s84, 0xe000
	s_nop 0
	global_load_lds_dwordx4 v[164:165], off
	s_waitcnt vmcnt(8)
	s_waitcnt lgkmcnt(0)
	s_barrier
	s_waitcnt lgkmcnt(0)
	v_mfma_f32_16x16x32_bf16 v[128:131], v[132:135], v[182:185], v[128:131]
	v_mfma_f32_16x16x32_bf16 v[124:127], v[152:155], v[182:185], v[124:127]
	v_mfma_f32_16x16x32_bf16 v[112:115], v[132:135], v[190:193], v[112:115]
	v_mfma_f32_16x16x32_bf16 v[108:111], v[152:155], v[190:193], v[108:111]
	v_mfma_f32_16x16x32_bf16 v[96:99], v[132:135], v[198:201], v[96:99]
	v_mfma_f32_16x16x32_bf16 v[92:95], v[152:155], v[198:201], v[92:95]
	v_mfma_f32_16x16x32_bf16 v[80:83], v[132:135], v[218:221], v[80:83]
	v_mfma_f32_16x16x32_bf16 v[76:79], v[152:155], v[218:221], v[76:79]
	v_mfma_f32_16x16x32_bf16 v[128:131], v[148:151], v[186:189], v[128:131]
	v_mfma_f32_16x16x32_bf16 v[124:127], v[156:159], v[186:189], v[124:127]
	v_mfma_f32_16x16x32_bf16 v[112:115], v[148:151], v[194:197], v[112:115]
	v_mfma_f32_16x16x32_bf16 v[108:111], v[156:159], v[194:197], v[108:111]
	v_mfma_f32_16x16x32_bf16 v[96:99], v[148:151], v[202:205], v[96:99]
	v_mfma_f32_16x16x32_bf16 v[92:95], v[156:159], v[202:205], v[92:95]
	v_mfma_f32_16x16x32_bf16 v[80:83], v[148:151], v[222:225], v[80:83]
	v_mfma_f32_16x16x32_bf16 v[76:79], v[156:159], v[222:225], v[76:79]
	v_mfma_f32_16x16x32_bf16 v[120:123], v[160:163], v[182:185], v[120:123]
	v_mfma_f32_16x16x32_bf16 v[116:119], v[174:177], v[182:185], v[116:119]
	v_mfma_f32_16x16x32_bf16 v[104:107], v[160:163], v[190:193], v[104:107]
	v_mfma_f32_16x16x32_bf16 v[100:103], v[174:177], v[190:193], v[100:103]
	v_mfma_f32_16x16x32_bf16 v[88:91], v[160:163], v[198:201], v[88:91]
	v_mfma_f32_16x16x32_bf16 v[84:87], v[174:177], v[198:201], v[84:87]
	v_mfma_f32_16x16x32_bf16 v[72:75], v[160:163], v[218:221], v[72:75]
	v_mfma_f32_16x16x32_bf16 v[68:71], v[174:177], v[218:221], v[68:71]
	v_mfma_f32_16x16x32_bf16 v[120:123], v[170:173], v[186:189], v[120:123]
	v_mfma_f32_16x16x32_bf16 v[116:119], v[178:181], v[186:189], v[116:119]
	v_mfma_f32_16x16x32_bf16 v[104:107], v[170:173], v[194:197], v[104:107]
	v_mfma_f32_16x16x32_bf16 v[100:103], v[178:181], v[194:197], v[100:103]
	v_mfma_f32_16x16x32_bf16 v[88:91], v[170:173], v[202:205], v[88:91]
	v_mfma_f32_16x16x32_bf16 v[84:87], v[178:181], v[202:205], v[84:87]
	v_mfma_f32_16x16x32_bf16 v[72:75], v[170:173], v[222:225], v[72:75]
	v_mfma_f32_16x16x32_bf16 v[68:71], v[178:181], v[222:225], v[68:71]
	s_barrier
	s_add_i32 s18, s61, s83
	v_lshl_add_u64 v[164:165], s[6:7], 0, v[138:139]
	s_mov_b32 m0, s18
	ds_read_b128 v[182:185], v168 offset:16384
	ds_read_b128 v[186:189], v168 offset:17408
	ds_read_b128 v[190:193], v168 offset:18432
	ds_read_b128 v[194:197], v168 offset:19456
	ds_read_b128 v[198:201], v168 offset:20480
	ds_read_b128 v[202:205], v168 offset:21504
	ds_read_b128 v[218:221], v168 offset:22528
	ds_read_b128 v[222:225], v168 offset:23552
	global_load_lds_dwordx4 v[164:165], off
	s_add_i32 m0, s18, 0x2000
	s_add_u32 s18, s6, 0x40000
	v_lshl_add_u64 v[206:207], s[6:7], 0, v[142:143]
	s_addc_u32 s19, s7, 0
	s_add_i32 s21, s77, s83
	global_load_lds_dwordx4 v[206:207], off
	v_lshl_add_u64 v[210:211], s[18:19], 0, v[138:139]
	s_mov_b32 m0, s21
	v_lshl_add_u64 v[212:213], s[8:9], 0, v[140:141]
	global_load_lds_dwordx4 v[210:211], off
	v_lshl_add_u64 v[210:211], s[18:19], 0, v[142:143]
	s_add_i32 m0, s21, 0x2000
	s_nop 0
	global_load_lds_dwordx4 v[210:211], off
	v_lshl_add_u64 v[210:211], s[8:9], 0, v[136:137]
	s_mov_b32 m0, s84
	s_nop 0
	global_load_lds_dwordx4 v[210:211], off
	s_mov_b32 m0, s85
	s_nop 0
	global_load_lds_dwordx4 v[212:213], off
	s_waitcnt vmcnt(8)
	s_waitcnt lgkmcnt(0)
	s_barrier
	s_waitcnt lgkmcnt(0)
	v_mfma_f32_16x16x32_bf16 v[64:67], v[132:135], v[182:185], v[64:67]
	v_mfma_f32_16x16x32_bf16 v[60:63], v[152:155], v[182:185], v[60:63]
	v_mfma_f32_16x16x32_bf16 v[48:51], v[132:135], v[190:193], v[48:51]
	v_mfma_f32_16x16x32_bf16 v[44:47], v[152:155], v[190:193], v[44:47]
	v_mfma_f32_16x16x32_bf16 v[32:35], v[132:135], v[198:201], v[32:35]
	v_mfma_f32_16x16x32_bf16 v[28:31], v[152:155], v[198:201], v[28:31]
	v_mfma_f32_16x16x32_bf16 v[16:19], v[132:135], v[218:221], v[16:19]
	v_mfma_f32_16x16x32_bf16 v[12:15], v[152:155], v[218:221], v[12:15]
	v_mfma_f32_16x16x32_bf16 v[64:67], v[148:151], v[186:189], v[64:67]
	v_mfma_f32_16x16x32_bf16 v[60:63], v[156:159], v[186:189], v[60:63]
	v_mfma_f32_16x16x32_bf16 v[48:51], v[148:151], v[194:197], v[48:51]
	v_mfma_f32_16x16x32_bf16 v[44:47], v[156:159], v[194:197], v[44:47]
	v_mfma_f32_16x16x32_bf16 v[32:35], v[148:151], v[202:205], v[32:35]
	v_mfma_f32_16x16x32_bf16 v[28:31], v[156:159], v[202:205], v[28:31]
	v_mfma_f32_16x16x32_bf16 v[16:19], v[148:151], v[222:225], v[16:19]
	v_mfma_f32_16x16x32_bf16 v[12:15], v[156:159], v[222:225], v[12:15]
	v_mfma_f32_16x16x32_bf16 v[56:59], v[160:163], v[182:185], v[56:59]
	v_mfma_f32_16x16x32_bf16 v[52:55], v[174:177], v[182:185], v[52:55]
	v_mfma_f32_16x16x32_bf16 v[40:43], v[160:163], v[190:193], v[40:43]
	v_mfma_f32_16x16x32_bf16 v[36:39], v[174:177], v[190:193], v[36:39]
	v_mfma_f32_16x16x32_bf16 v[24:27], v[160:163], v[198:201], v[24:27]
	v_mfma_f32_16x16x32_bf16 v[20:23], v[174:177], v[198:201], v[20:23]
	v_mfma_f32_16x16x32_bf16 v[8:11], v[160:163], v[218:221], v[8:11]
	v_mfma_f32_16x16x32_bf16 v[4:7], v[174:177], v[218:221], v[4:7]
	v_mfma_f32_16x16x32_bf16 v[56:59], v[170:173], v[186:189], v[56:59]
	v_mfma_f32_16x16x32_bf16 v[52:55], v[178:181], v[186:189], v[52:55]
	v_mfma_f32_16x16x32_bf16 v[40:43], v[170:173], v[194:197], v[40:43]
	v_mfma_f32_16x16x32_bf16 v[36:39], v[178:181], v[194:197], v[36:39]
	v_mfma_f32_16x16x32_bf16 v[24:27], v[170:173], v[202:205], v[24:27]
	v_mfma_f32_16x16x32_bf16 v[20:23], v[178:181], v[202:205], v[20:23]
	v_mfma_f32_16x16x32_bf16 v[8:11], v[170:173], v[222:225], v[8:11]
	v_mfma_f32_16x16x32_bf16 v[4:7], v[178:181], v[222:225], v[4:7]
	s_barrier
	s_add_i32 s79, 0, 0x18000
	v_add_u32_e32 v2, s79, v167
	s_add_i32 s80, 0, 0x1c000
	ds_read_b128 v[132:135], v2
	ds_read_b128 v[148:151], v2 offset:1024
	ds_read_b128 v[152:155], v2 offset:2048
	ds_read_b128 v[156:159], v2 offset:3072
	v_add_u32_e32 v2, s80, v167
	ds_read_b128 v[160:163], v2
	ds_read_b128 v[170:173], v2 offset:1024
	ds_read_b128 v[174:177], v2 offset:2048
	ds_read_b128 v[178:181], v2 offset:3072
	s_add_u32 s8, s8, 0x40000
	s_addc_u32 s9, s9, 0
	s_mov_b32 m0, s68
	v_lshl_add_u64 v[226:227], s[8:9], 0, v[136:137]
	ds_read_b128 v[182:185], v168 offset:32768
	ds_read_b128 v[186:189], v168 offset:33792
	ds_read_b128 v[190:193], v168 offset:34816
	ds_read_b128 v[194:197], v168 offset:35840
	ds_read_b128 v[198:201], v168 offset:36864
	ds_read_b128 v[202:205], v168 offset:37888
	ds_read_b128 v[218:221], v168 offset:38912
	ds_read_b128 v[222:225], v168 offset:39936
	global_load_lds_dwordx4 v[226:227], off
	v_lshl_add_u64 v[226:227], s[8:9], 0, v[140:141]
	s_mov_b32 m0, s69
	s_nop 0
	global_load_lds_dwordx4 v[226:227], off
	s_waitcnt vmcnt(8)
	s_waitcnt lgkmcnt(0)
	s_barrier
	s_waitcnt lgkmcnt(0)
	v_mfma_f32_16x16x32_bf16 v[128:131], v[132:135], v[182:185], v[128:131]
	v_mfma_f32_16x16x32_bf16 v[124:127], v[152:155], v[182:185], v[124:127]
	v_mfma_f32_16x16x32_bf16 v[112:115], v[132:135], v[190:193], v[112:115]
	v_mfma_f32_16x16x32_bf16 v[108:111], v[152:155], v[190:193], v[108:111]
	v_mfma_f32_16x16x32_bf16 v[96:99], v[132:135], v[198:201], v[96:99]
	v_mfma_f32_16x16x32_bf16 v[92:95], v[152:155], v[198:201], v[92:95]
	v_mfma_f32_16x16x32_bf16 v[80:83], v[132:135], v[218:221], v[80:83]
	v_mfma_f32_16x16x32_bf16 v[76:79], v[152:155], v[218:221], v[76:79]
	v_mfma_f32_16x16x32_bf16 v[128:131], v[148:151], v[186:189], v[128:131]
	v_mfma_f32_16x16x32_bf16 v[124:127], v[156:159], v[186:189], v[124:127]
	v_mfma_f32_16x16x32_bf16 v[112:115], v[148:151], v[194:197], v[112:115]
	v_mfma_f32_16x16x32_bf16 v[108:111], v[156:159], v[194:197], v[108:111]
	v_mfma_f32_16x16x32_bf16 v[96:99], v[148:151], v[202:205], v[96:99]
	v_mfma_f32_16x16x32_bf16 v[92:95], v[156:159], v[202:205], v[92:95]
	v_mfma_f32_16x16x32_bf16 v[80:83], v[148:151], v[222:225], v[80:83]
	v_mfma_f32_16x16x32_bf16 v[76:79], v[156:159], v[222:225], v[76:79]
	v_mfma_f32_16x16x32_bf16 v[120:123], v[160:163], v[182:185], v[120:123]
	v_mfma_f32_16x16x32_bf16 v[116:119], v[174:177], v[182:185], v[116:119]
	v_mfma_f32_16x16x32_bf16 v[104:107], v[160:163], v[190:193], v[104:107]
	v_mfma_f32_16x16x32_bf16 v[100:103], v[174:177], v[190:193], v[100:103]
	v_mfma_f32_16x16x32_bf16 v[88:91], v[160:163], v[198:201], v[88:91]
	v_mfma_f32_16x16x32_bf16 v[84:87], v[174:177], v[198:201], v[84:87]
	v_mfma_f32_16x16x32_bf16 v[72:75], v[160:163], v[218:221], v[72:75]
	v_mfma_f32_16x16x32_bf16 v[68:71], v[174:177], v[218:221], v[68:71]
	v_mfma_f32_16x16x32_bf16 v[120:123], v[170:173], v[186:189], v[120:123]
	v_mfma_f32_16x16x32_bf16 v[116:119], v[178:181], v[186:189], v[116:119]
	v_mfma_f32_16x16x32_bf16 v[104:107], v[170:173], v[194:197], v[104:107]
	v_mfma_f32_16x16x32_bf16 v[100:103], v[178:181], v[194:197], v[100:103]
	v_mfma_f32_16x16x32_bf16 v[88:91], v[170:173], v[202:205], v[88:91]
	v_mfma_f32_16x16x32_bf16 v[84:87], v[178:181], v[202:205], v[84:87]
	v_mfma_f32_16x16x32_bf16 v[72:75], v[170:173], v[222:225], v[72:75]
	v_mfma_f32_16x16x32_bf16 v[68:71], v[178:181], v[222:225], v[68:71]
	s_barrier
	s_add_i32 s8, s79, s83
	v_lshl_add_u64 v[164:165], v[164:165], 0, s[56:57]
	s_mov_b32 m0, s8
	ds_read_b128 v[182:185], v168 offset:49152
	ds_read_b128 v[186:189], v168 offset:50176
	ds_read_b128 v[190:193], v168 offset:51200
	ds_read_b128 v[194:197], v168 offset:52224
	ds_read_b128 v[198:201], v168 offset:53248
	ds_read_b128 v[202:205], v168 offset:54272
	ds_read_b128 v[218:221], v168 offset:55296
	ds_read_b128 v[222:225], v168 offset:56320
	global_load_lds_dwordx4 v[164:165], off
	s_add_i32 m0, s8, 0x2000
	s_add_u32 s6, s6, 0x40080
	v_lshl_add_u64 v[164:165], v[206:207], 0, s[56:57]
	s_addc_u32 s7, s7, 0
	s_add_i32 s8, s80, s83
	global_load_lds_dwordx4 v[164:165], off
	v_lshl_add_u64 v[164:165], s[6:7], 0, v[138:139]
	s_mov_b32 m0, s8
	s_nop 0
	global_load_lds_dwordx4 v[164:165], off
	v_lshl_add_u64 v[164:165], s[6:7], 0, v[142:143]
	s_add_i32 m0, s8, 0x2000
	s_nop 0
	global_load_lds_dwordx4 v[164:165], off
	v_lshl_add_u64 v[164:165], v[210:211], 0, s[56:57]
	s_mov_b32 m0, s72
	s_nop 0
	global_load_lds_dwordx4 v[164:165], off
	v_lshl_add_u64 v[164:165], v[212:213], 0, s[56:57]
	s_mov_b32 m0, s73
	s_nop 0
	global_load_lds_dwordx4 v[164:165], off
	s_waitcnt vmcnt(8)
	s_waitcnt lgkmcnt(0)
	s_barrier
	s_waitcnt lgkmcnt(0)
	v_mfma_f32_16x16x32_bf16 v[64:67], v[132:135], v[182:185], v[64:67]
	v_mfma_f32_16x16x32_bf16 v[60:63], v[152:155], v[182:185], v[60:63]
	v_mfma_f32_16x16x32_bf16 v[48:51], v[132:135], v[190:193], v[48:51]
	v_mfma_f32_16x16x32_bf16 v[44:47], v[152:155], v[190:193], v[44:47]
	v_mfma_f32_16x16x32_bf16 v[32:35], v[132:135], v[198:201], v[32:35]
	v_mfma_f32_16x16x32_bf16 v[28:31], v[152:155], v[198:201], v[28:31]
	v_mfma_f32_16x16x32_bf16 v[16:19], v[132:135], v[218:221], v[16:19]
	v_mfma_f32_16x16x32_bf16 v[12:15], v[152:155], v[218:221], v[12:15]
	v_mfma_f32_16x16x32_bf16 v[64:67], v[148:151], v[186:189], v[64:67]
	v_mfma_f32_16x16x32_bf16 v[60:63], v[156:159], v[186:189], v[60:63]
	v_mfma_f32_16x16x32_bf16 v[48:51], v[148:151], v[194:197], v[48:51]
	v_mfma_f32_16x16x32_bf16 v[44:47], v[156:159], v[194:197], v[44:47]
	v_mfma_f32_16x16x32_bf16 v[32:35], v[148:151], v[202:205], v[32:35]
	v_mfma_f32_16x16x32_bf16 v[28:31], v[156:159], v[202:205], v[28:31]
	v_mfma_f32_16x16x32_bf16 v[16:19], v[148:151], v[222:225], v[16:19]
	v_mfma_f32_16x16x32_bf16 v[12:15], v[156:159], v[222:225], v[12:15]
	v_mfma_f32_16x16x32_bf16 v[56:59], v[160:163], v[182:185], v[56:59]
	v_mfma_f32_16x16x32_bf16 v[52:55], v[174:177], v[182:185], v[52:55]
	v_mfma_f32_16x16x32_bf16 v[40:43], v[160:163], v[190:193], v[40:43]
	v_mfma_f32_16x16x32_bf16 v[36:39], v[174:177], v[190:193], v[36:39]
	v_mfma_f32_16x16x32_bf16 v[24:27], v[160:163], v[198:201], v[24:27]
	v_mfma_f32_16x16x32_bf16 v[20:23], v[174:177], v[198:201], v[20:23]
	v_mfma_f32_16x16x32_bf16 v[8:11], v[160:163], v[218:221], v[8:11]
	v_mfma_f32_16x16x32_bf16 v[4:7], v[174:177], v[218:221], v[4:7]
	v_mfma_f32_16x16x32_bf16 v[56:59], v[170:173], v[186:189], v[56:59]
	v_mfma_f32_16x16x32_bf16 v[52:55], v[178:181], v[186:189], v[52:55]
	v_mfma_f32_16x16x32_bf16 v[40:43], v[170:173], v[194:197], v[40:43]
	v_mfma_f32_16x16x32_bf16 v[36:39], v[178:181], v[194:197], v[36:39]
	v_mfma_f32_16x16x32_bf16 v[24:27], v[170:173], v[202:205], v[24:27]
	v_mfma_f32_16x16x32_bf16 v[20:23], v[178:181], v[202:205], v[20:23]
	v_mfma_f32_16x16x32_bf16 v[8:11], v[170:173], v[222:225], v[8:11]
	v_mfma_f32_16x16x32_bf16 v[4:7], v[178:181], v[222:225], v[4:7]
	s_barrier
	s_add_i32 s17, s17, 2
	s_add_u32 s4, s4, 0x100
	s_addc_u32 s5, s5, 0
	s_add_u32 s15, s15, 0x100
	s_addc_u32 s16, s16, 0
	s_cmp_gt_u32 s17, 13
	s_cbranch_scc0 .LBB0_541
	s_and_b64 vcc, exec, s[58:59]
	s_cbranch_vccz .LBB0_544
	s_barrier

.LBB0_985:
	v_add_u32_e32 v158, s61, v144
	v_add_u32_e32 v174, s77, v144
	s_add_u32 s8, s20, s6
	ds_read_b128 v[146:149], v158
	ds_read_b128 v[150:153], v158 offset:1024
	ds_read_b128 v[154:157], v158 offset:2048
	ds_read_b128 v[158:161], v158 offset:3072
	ds_read_b128 v[162:165], v174
	ds_read_b128 v[166:169], v174 offset:1024
	ds_read_b128 v[170:173], v174 offset:2048
	ds_read_b128 v[174:177], v174 offset:3072
	s_addc_u32 s9, s21, s7
	s_add_u32 s8, s8, 0x4000100
	s_addc_u32 s9, s9, 0
	s_add_u32 s25, s22, s6
	s_addc_u32 s26, s23, s7
	s_cmpk_eq_i32 s6, 0x700
	s_cselect_b32 s11, s3, s9
	s_cselect_b32 s10, s2, s8
	s_cselect_b32 s9, s1, s26
	s_cselect_b32 s8, s0, s25
	v_lshl_add_u64 v[206:207], v[140:141], 0, s[6:7]
	s_add_i32 m0, s5, 0xc000
	ds_read_b128 v[178:181], v145
	ds_read_b128 v[182:185], v145 offset:1024
	ds_read_b128 v[186:189], v145 offset:2048
	ds_read_b128 v[190:193], v145 offset:3072
	ds_read_b128 v[194:197], v145 offset:4096
	ds_read_b128 v[198:201], v145 offset:5120
	ds_read_b128 v[202:205], v145 offset:6144
	ds_read_b128 v[218:221], v145 offset:7168
	global_load_lds_dwordx4 v[206:207], off
	v_lshl_add_u64 v[206:207], v[142:143], 0, s[6:7]
	s_add_i32 m0, s5, 0xe000
	s_nop 0
	global_load_lds_dwordx4 v[206:207], off
	s_waitcnt vmcnt(8)
	s_waitcnt lgkmcnt(0)
	s_barrier
	s_waitcnt lgkmcnt(0)
	v_mfma_f32_16x16x32_bf16 v[128:131], v[146:149], v[178:181], v[128:131]
	v_mfma_f32_16x16x32_bf16 v[124:127], v[154:157], v[178:181], v[124:127]
	v_mfma_f32_16x16x32_bf16 v[112:115], v[146:149], v[186:189], v[112:115]
	v_mfma_f32_16x16x32_bf16 v[108:111], v[154:157], v[186:189], v[108:111]
	v_mfma_f32_16x16x32_bf16 v[96:99], v[146:149], v[194:197], v[96:99]
	v_mfma_f32_16x16x32_bf16 v[92:95], v[154:157], v[194:197], v[92:95]
	v_mfma_f32_16x16x32_bf16 v[80:83], v[146:149], v[202:205], v[80:83]
	v_mfma_f32_16x16x32_bf16 v[76:79], v[154:157], v[202:205], v[76:79]
	v_mfma_f32_16x16x32_bf16 v[128:131], v[150:153], v[182:185], v[128:131]
	v_mfma_f32_16x16x32_bf16 v[124:127], v[158:161], v[182:185], v[124:127]
	v_mfma_f32_16x16x32_bf16 v[112:115], v[150:153], v[190:193], v[112:115]
	v_mfma_f32_16x16x32_bf16 v[108:111], v[158:161], v[190:193], v[108:111]
	v_mfma_f32_16x16x32_bf16 v[96:99], v[150:153], v[198:201], v[96:99]
	v_mfma_f32_16x16x32_bf16 v[92:95], v[158:161], v[198:201], v[92:95]
	v_mfma_f32_16x16x32_bf16 v[80:83], v[150:153], v[218:221], v[80:83]
	v_mfma_f32_16x16x32_bf16 v[76:79], v[158:161], v[218:221], v[76:79]
	v_mfma_f32_16x16x32_bf16 v[120:123], v[162:165], v[178:181], v[120:123]
	v_mfma_f32_16x16x32_bf16 v[116:119], v[170:173], v[178:181], v[116:119]
	v_mfma_f32_16x16x32_bf16 v[104:107], v[162:165], v[186:189], v[104:107]
	v_mfma_f32_16x16x32_bf16 v[100:103], v[170:173], v[186:189], v[100:103]
	v_mfma_f32_16x16x32_bf16 v[88:91], v[162:165], v[194:197], v[88:91]
	v_mfma_f32_16x16x32_bf16 v[84:87], v[170:173], v[194:197], v[84:87]
	v_mfma_f32_16x16x32_bf16 v[72:75], v[162:165], v[202:205], v[72:75]
	v_mfma_f32_16x16x32_bf16 v[68:71], v[170:173], v[202:205], v[68:71]
	v_mfma_f32_16x16x32_bf16 v[120:123], v[166:169], v[182:185], v[120:123]
	v_mfma_f32_16x16x32_bf16 v[116:119], v[174:177], v[182:185], v[116:119]
	v_mfma_f32_16x16x32_bf16 v[104:107], v[166:169], v[190:193], v[104:107]
	v_mfma_f32_16x16x32_bf16 v[100:103], v[174:177], v[190:193], v[100:103]
	v_mfma_f32_16x16x32_bf16 v[88:91], v[166:169], v[198:201], v[88:91]
	v_mfma_f32_16x16x32_bf16 v[84:87], v[174:177], v[198:201], v[84:87]
	v_mfma_f32_16x16x32_bf16 v[72:75], v[166:169], v[218:221], v[72:75]
	v_mfma_f32_16x16x32_bf16 v[68:71], v[174:177], v[218:221], v[68:71]
	s_barrier
	s_add_i32 s25, s61, s13
	v_lshl_add_u64 v[206:207], s[8:9], 0, v[136:137]
	s_mov_b32 m0, s25
	ds_read_b128 v[178:181], v145 offset:16384
	ds_read_b128 v[182:185], v145 offset:17408
	ds_read_b128 v[186:189], v145 offset:18432
	ds_read_b128 v[190:193], v145 offset:19456
	ds_read_b128 v[194:197], v145 offset:20480
	ds_read_b128 v[198:201], v145 offset:21504
	ds_read_b128 v[202:205], v145 offset:22528
	ds_read_b128 v[218:221], v145 offset:23552
	global_load_lds_dwordx4 v[206:207], off
	s_add_i32 m0, s25, 0x2000
	s_add_u32 s26, s8, 0x40000
	v_lshl_add_u64 v[210:211], s[8:9], 0, v[132:133]
	s_addc_u32 s27, s9, 0
	s_add_i32 s25, s77, s13
	global_load_lds_dwordx4 v[210:211], off
	v_lshl_add_u64 v[212:213], s[26:27], 0, v[136:137]
	s_mov_b32 m0, s25
	v_lshl_add_u64 v[222:223], s[10:11], 0, v[134:135]
	global_load_lds_dwordx4 v[212:213], off
	v_lshl_add_u64 v[212:213], s[26:27], 0, v[132:133]
	s_add_i32 m0, s25, 0x2000
	s_nop 0
	global_load_lds_dwordx4 v[212:213], off
	v_lshl_add_u64 v[212:213], s[10:11], 0, v[138:139]
	s_mov_b32 m0, s5
	s_nop 0
	global_load_lds_dwordx4 v[212:213], off
	s_mov_b32 m0, s15
	s_nop 0
	global_load_lds_dwordx4 v[222:223], off
	s_waitcnt vmcnt(8)
	s_waitcnt lgkmcnt(0)
	s_barrier
	s_waitcnt lgkmcnt(0)
	v_mfma_f32_16x16x32_bf16 v[64:67], v[146:149], v[178:181], v[64:67]
	v_mfma_f32_16x16x32_bf16 v[60:63], v[154:157], v[178:181], v[60:63]
	v_mfma_f32_16x16x32_bf16 v[48:51], v[146:149], v[186:189], v[48:51]
	v_mfma_f32_16x16x32_bf16 v[44:47], v[154:157], v[186:189], v[44:47]
	v_mfma_f32_16x16x32_bf16 v[32:35], v[146:149], v[194:197], v[32:35]
	v_mfma_f32_16x16x32_bf16 v[28:31], v[154:157], v[194:197], v[28:31]
	v_mfma_f32_16x16x32_bf16 v[16:19], v[146:149], v[202:205], v[16:19]
	v_mfma_f32_16x16x32_bf16 v[12:15], v[154:157], v[202:205], v[12:15]
	v_mfma_f32_16x16x32_bf16 v[64:67], v[150:153], v[182:185], v[64:67]
	v_mfma_f32_16x16x32_bf16 v[60:63], v[158:161], v[182:185], v[60:63]
	v_mfma_f32_16x16x32_bf16 v[48:51], v[150:153], v[190:193], v[48:51]
	v_mfma_f32_16x16x32_bf16 v[44:47], v[158:161], v[190:193], v[44:47]
	v_mfma_f32_16x16x32_bf16 v[32:35], v[150:153], v[198:201], v[32:35]
	v_mfma_f32_16x16x32_bf16 v[28:31], v[158:161], v[198:201], v[28:31]
	v_mfma_f32_16x16x32_bf16 v[16:19], v[150:153], v[218:221], v[16:19]
	v_mfma_f32_16x16x32_bf16 v[12:15], v[158:161], v[218:221], v[12:15]
	v_mfma_f32_16x16x32_bf16 v[56:59], v[162:165], v[178:181], v[56:59]
	v_mfma_f32_16x16x32_bf16 v[52:55], v[170:173], v[178:181], v[52:55]
	v_mfma_f32_16x16x32_bf16 v[40:43], v[162:165], v[186:189], v[40:43]
	v_mfma_f32_16x16x32_bf16 v[36:39], v[170:173], v[186:189], v[36:39]
	v_mfma_f32_16x16x32_bf16 v[24:27], v[162:165], v[194:197], v[24:27]
	v_mfma_f32_16x16x32_bf16 v[20:23], v[170:173], v[194:197], v[20:23]
	v_mfma_f32_16x16x32_bf16 v[8:11], v[162:165], v[202:205], v[8:11]
	v_mfma_f32_16x16x32_bf16 v[4:7], v[170:173], v[202:205], v[4:7]
	v_mfma_f32_16x16x32_bf16 v[56:59], v[166:169], v[182:185], v[56:59]
	v_mfma_f32_16x16x32_bf16 v[52:55], v[174:177], v[182:185], v[52:55]
	v_mfma_f32_16x16x32_bf16 v[40:43], v[166:169], v[190:193], v[40:43]
	v_mfma_f32_16x16x32_bf16 v[36:39], v[174:177], v[190:193], v[36:39]
	v_mfma_f32_16x16x32_bf16 v[24:27], v[166:169], v[198:201], v[24:27]
	v_mfma_f32_16x16x32_bf16 v[20:23], v[174:177], v[198:201], v[20:23]
	v_mfma_f32_16x16x32_bf16 v[8:11], v[166:169], v[218:221], v[8:11]
	v_mfma_f32_16x16x32_bf16 v[4:7], v[174:177], v[218:221], v[4:7]
	s_barrier
	v_add_u32_e32 v158, s79, v144
	v_add_u32_e32 v174, s80, v144
	ds_read_b128 v[146:149], v158
	ds_read_b128 v[150:153], v158 offset:1024
	ds_read_b128 v[154:157], v158 offset:2048
	ds_read_b128 v[158:161], v158 offset:3072
	ds_read_b128 v[162:165], v174
	ds_read_b128 v[166:169], v174 offset:1024
	ds_read_b128 v[170:173], v174 offset:2048
	ds_read_b128 v[174:177], v174 offset:3072
	s_add_u32 s10, s10, 0x40000
	s_addc_u32 s11, s11, 0
	s_mov_b32 m0, s16
	v_lshl_add_u64 v[224:225], s[10:11], 0, v[138:139]
	ds_read_b128 v[178:181], v145 offset:32768
	ds_read_b128 v[182:185], v145 offset:33792
	ds_read_b128 v[186:189], v145 offset:34816
	ds_read_b128 v[190:193], v145 offset:35840
	ds_read_b128 v[194:197], v145 offset:36864
	ds_read_b128 v[198:201], v145 offset:37888
	ds_read_b128 v[202:205], v145 offset:38912
	ds_read_b128 v[218:221], v145 offset:39936
	global_load_lds_dwordx4 v[224:225], off
	v_lshl_add_u64 v[224:225], s[10:11], 0, v[134:135]
	s_mov_b32 m0, s17
	s_nop 0
	global_load_lds_dwordx4 v[224:225], off
	s_waitcnt vmcnt(8)
	s_waitcnt lgkmcnt(0)
	s_barrier
	s_waitcnt lgkmcnt(0)
	v_mfma_f32_16x16x32_bf16 v[128:131], v[146:149], v[178:181], v[128:131]
	v_mfma_f32_16x16x32_bf16 v[124:127], v[154:157], v[178:181], v[124:127]
	v_mfma_f32_16x16x32_bf16 v[112:115], v[146:149], v[186:189], v[112:115]
	v_mfma_f32_16x16x32_bf16 v[108:111], v[154:157], v[186:189], v[108:111]
	v_mfma_f32_16x16x32_bf16 v[96:99], v[146:149], v[194:197], v[96:99]
	v_mfma_f32_16x16x32_bf16 v[92:95], v[154:157], v[194:197], v[92:95]
	v_mfma_f32_16x16x32_bf16 v[80:83], v[146:149], v[202:205], v[80:83]
	v_mfma_f32_16x16x32_bf16 v[76:79], v[154:157], v[202:205], v[76:79]
	v_mfma_f32_16x16x32_bf16 v[128:131], v[150:153], v[182:185], v[128:131]
	v_mfma_f32_16x16x32_bf16 v[124:127], v[158:161], v[182:185], v[124:127]
	v_mfma_f32_16x16x32_bf16 v[112:115], v[150:153], v[190:193], v[112:115]
	v_mfma_f32_16x16x32_bf16 v[108:111], v[158:161], v[190:193], v[108:111]
	v_mfma_f32_16x16x32_bf16 v[96:99], v[150:153], v[198:201], v[96:99]
	v_mfma_f32_16x16x32_bf16 v[92:95], v[158:161], v[198:201], v[92:95]
	v_mfma_f32_16x16x32_bf16 v[80:83], v[150:153], v[218:221], v[80:83]
	v_mfma_f32_16x16x32_bf16 v[76:79], v[158:161], v[218:221], v[76:79]
	v_mfma_f32_16x16x32_bf16 v[120:123], v[162:165], v[178:181], v[120:123]
	v_mfma_f32_16x16x32_bf16 v[116:119], v[170:173], v[178:181], v[116:119]
	v_mfma_f32_16x16x32_bf16 v[104:107], v[162:165], v[186:189], v[104:107]
	v_mfma_f32_16x16x32_bf16 v[100:103], v[170:173], v[186:189], v[100:103]
	v_mfma_f32_16x16x32_bf16 v[88:91], v[162:165], v[194:197], v[88:91]
	v_mfma_f32_16x16x32_bf16 v[84:87], v[170:173], v[194:197], v[84:87]
	v_mfma_f32_16x16x32_bf16 v[72:75], v[162:165], v[202:205], v[72:75]
	v_mfma_f32_16x16x32_bf16 v[68:71], v[170:173], v[202:205], v[68:71]
	v_mfma_f32_16x16x32_bf16 v[120:123], v[166:169], v[182:185], v[120:123]
	v_mfma_f32_16x16x32_bf16 v[116:119], v[174:177], v[182:185], v[116:119]
	v_mfma_f32_16x16x32_bf16 v[104:107], v[166:169], v[190:193], v[104:107]
	v_mfma_f32_16x16x32_bf16 v[100:103], v[174:177], v[190:193], v[100:103]
	v_mfma_f32_16x16x32_bf16 v[88:91], v[166:169], v[198:201], v[88:91]
	v_mfma_f32_16x16x32_bf16 v[84:87], v[174:177], v[198:201], v[84:87]
	v_mfma_f32_16x16x32_bf16 v[72:75], v[166:169], v[218:221], v[72:75]
	v_mfma_f32_16x16x32_bf16 v[68:71], v[174:177], v[218:221], v[68:71]
	s_barrier
	s_add_i32 s10, s79, s13
	v_lshl_add_u64 v[206:207], v[206:207], 0, s[56:57]
	s_mov_b32 m0, s10
	ds_read_b128 v[178:181], v145 offset:49152
	ds_read_b128 v[182:185], v145 offset:50176
	ds_read_b128 v[186:189], v145 offset:51200
	ds_read_b128 v[190:193], v145 offset:52224
	ds_read_b128 v[194:197], v145 offset:53248
	ds_read_b128 v[198:201], v145 offset:54272
	ds_read_b128 v[202:205], v145 offset:55296
	ds_read_b128 v[218:221], v145 offset:56320
	global_load_lds_dwordx4 v[206:207], off
	s_add_i32 m0, s10, 0x2000
	s_add_u32 s8, s8, 0x40080
	v_lshl_add_u64 v[206:207], v[210:211], 0, s[56:57]
	s_addc_u32 s9, s9, 0
	s_add_i32 s10, s80, s13
	global_load_lds_dwordx4 v[206:207], off
	v_lshl_add_u64 v[206:207], s[8:9], 0, v[136:137]
	s_mov_b32 m0, s10
	s_nop 0
	global_load_lds_dwordx4 v[206:207], off
	v_lshl_add_u64 v[206:207], s[8:9], 0, v[132:133]
	s_add_i32 m0, s10, 0x2000
	s_nop 0
	global_load_lds_dwordx4 v[206:207], off
	v_lshl_add_u64 v[206:207], v[212:213], 0, s[56:57]
	s_mov_b32 m0, s18
	s_nop 0
	global_load_lds_dwordx4 v[206:207], off
	v_lshl_add_u64 v[206:207], v[222:223], 0, s[56:57]
	s_mov_b32 m0, s19
	s_nop 0
	global_load_lds_dwordx4 v[206:207], off
	s_waitcnt vmcnt(8)
	s_waitcnt lgkmcnt(0)
	s_barrier
	s_waitcnt lgkmcnt(0)
	v_mfma_f32_16x16x32_bf16 v[64:67], v[146:149], v[178:181], v[64:67]
	v_mfma_f32_16x16x32_bf16 v[60:63], v[154:157], v[178:181], v[60:63]
	v_mfma_f32_16x16x32_bf16 v[48:51], v[146:149], v[186:189], v[48:51]
	v_mfma_f32_16x16x32_bf16 v[44:47], v[154:157], v[186:189], v[44:47]
	v_mfma_f32_16x16x32_bf16 v[32:35], v[146:149], v[194:197], v[32:35]
	v_mfma_f32_16x16x32_bf16 v[28:31], v[154:157], v[194:197], v[28:31]
	v_mfma_f32_16x16x32_bf16 v[16:19], v[146:149], v[202:205], v[16:19]
	v_mfma_f32_16x16x32_bf16 v[12:15], v[154:157], v[202:205], v[12:15]
	v_mfma_f32_16x16x32_bf16 v[64:67], v[150:153], v[182:185], v[64:67]
	v_mfma_f32_16x16x32_bf16 v[60:63], v[158:161], v[182:185], v[60:63]
	v_mfma_f32_16x16x32_bf16 v[48:51], v[150:153], v[190:193], v[48:51]
	v_mfma_f32_16x16x32_bf16 v[44:47], v[158:161], v[190:193], v[44:47]
	v_mfma_f32_16x16x32_bf16 v[32:35], v[150:153], v[198:201], v[32:35]
	v_mfma_f32_16x16x32_bf16 v[28:31], v[158:161], v[198:201], v[28:31]
	v_mfma_f32_16x16x32_bf16 v[16:19], v[150:153], v[218:221], v[16:19]
	v_mfma_f32_16x16x32_bf16 v[12:15], v[158:161], v[218:221], v[12:15]
	v_mfma_f32_16x16x32_bf16 v[56:59], v[162:165], v[178:181], v[56:59]
	v_mfma_f32_16x16x32_bf16 v[52:55], v[170:173], v[178:181], v[52:55]
	v_mfma_f32_16x16x32_bf16 v[40:43], v[162:165], v[186:189], v[40:43]
	v_mfma_f32_16x16x32_bf16 v[36:39], v[170:173], v[186:189], v[36:39]
	v_mfma_f32_16x16x32_bf16 v[24:27], v[162:165], v[194:197], v[24:27]
	v_mfma_f32_16x16x32_bf16 v[20:23], v[170:173], v[194:197], v[20:23]
	v_mfma_f32_16x16x32_bf16 v[8:11], v[162:165], v[202:205], v[8:11]
	v_mfma_f32_16x16x32_bf16 v[4:7], v[170:173], v[202:205], v[4:7]
	v_mfma_f32_16x16x32_bf16 v[56:59], v[166:169], v[182:185], v[56:59]
	v_mfma_f32_16x16x32_bf16 v[52:55], v[174:177], v[182:185], v[52:55]
	v_mfma_f32_16x16x32_bf16 v[40:43], v[166:169], v[190:193], v[40:43]
	v_mfma_f32_16x16x32_bf16 v[36:39], v[174:177], v[190:193], v[36:39]
	v_mfma_f32_16x16x32_bf16 v[24:27], v[166:169], v[198:201], v[24:27]
	v_mfma_f32_16x16x32_bf16 v[20:23], v[174:177], v[198:201], v[20:23]
	v_mfma_f32_16x16x32_bf16 v[8:11], v[166:169], v[218:221], v[8:11]
	v_mfma_f32_16x16x32_bf16 v[4:7], v[174:177], v[218:221], v[4:7]
	s_barrier
	s_add_i32 s24, s24, 2
	s_add_u32 s6, s6, 0x100
	s_addc_u32 s7, s7, 0
	s_cmp_gt_u32 s24, 13
	s_cbranch_scc0 .LBB0_985
	s_cmpk_lt_u32 s12, 0x100
	s_cbranch_scc0 .LBB0_988
	s_barrier

.LBB0_2100:
	v_add_u32_e32 v148, s61, v150
	ds_read_b128 v[144:147], v148
	ds_read_b128 v[152:155], v148 offset:1024
	ds_read_b128 v[156:159], v148 offset:2048
	ds_read_b128 v[160:163], v148 offset:3072
	v_add_u32_e32 v148, s77, v150
	ds_read_b128 v[164:167], v148
	ds_read_b128 v[168:171], v148 offset:1024
	ds_read_b128 v[172:175], v148 offset:2048
	ds_read_b128 v[176:179], v148 offset:3072
	s_add_u32 s6, s4, 0xfff00080
	s_addc_u32 s7, s5, -1
	s_cmp_eq_u32 s53, 12
	s_cselect_b32 s9, s31, s7
	s_cselect_b32 s8, s51, s6
	s_cselect_b32 s7, s21, s52
	s_cselect_b32 s6, s20, s29
	v_lshl_add_u64 v[148:149], s[4:5], 0, v[140:141]
	s_add_i32 m0, s19, 0xc000
	ds_read_b128 v[180:183], v151
	ds_read_b128 v[184:187], v151 offset:1024
	ds_read_b128 v[188:191], v151 offset:2048
	ds_read_b128 v[192:195], v151 offset:3072
	ds_read_b128 v[196:199], v151 offset:4096
	ds_read_b128 v[200:203], v151 offset:5120
	ds_read_b128 v[204:207], v151 offset:6144
	ds_read_b128 v[210:213], v151 offset:7168
	global_load_lds_dwordx4 v[148:149], off
	v_lshl_add_u64 v[148:149], s[4:5], 0, v[142:143]
	s_add_i32 m0, s19, 0xe000
	s_nop 0
	global_load_lds_dwordx4 v[148:149], off
	s_waitcnt vmcnt(8)
	s_waitcnt lgkmcnt(0)
	s_barrier
	s_waitcnt lgkmcnt(0)
	v_mfma_f32_16x16x32_bf16 v[128:131], v[144:147], v[180:183], v[128:131]
	v_mfma_f32_16x16x32_bf16 v[124:127], v[156:159], v[180:183], v[124:127]
	v_mfma_f32_16x16x32_bf16 v[112:115], v[144:147], v[188:191], v[112:115]
	v_mfma_f32_16x16x32_bf16 v[108:111], v[156:159], v[188:191], v[108:111]
	v_mfma_f32_16x16x32_bf16 v[96:99], v[144:147], v[196:199], v[96:99]
	v_mfma_f32_16x16x32_bf16 v[92:95], v[156:159], v[196:199], v[92:95]
	v_mfma_f32_16x16x32_bf16 v[80:83], v[144:147], v[204:207], v[80:83]
	v_mfma_f32_16x16x32_bf16 v[76:79], v[156:159], v[204:207], v[76:79]
	v_mfma_f32_16x16x32_bf16 v[128:131], v[152:155], v[184:187], v[128:131]
	v_mfma_f32_16x16x32_bf16 v[124:127], v[160:163], v[184:187], v[124:127]
	v_mfma_f32_16x16x32_bf16 v[112:115], v[152:155], v[192:195], v[112:115]
	v_mfma_f32_16x16x32_bf16 v[108:111], v[160:163], v[192:195], v[108:111]
	v_mfma_f32_16x16x32_bf16 v[96:99], v[152:155], v[200:203], v[96:99]
	v_mfma_f32_16x16x32_bf16 v[92:95], v[160:163], v[200:203], v[92:95]
	v_mfma_f32_16x16x32_bf16 v[80:83], v[152:155], v[210:213], v[80:83]
	v_mfma_f32_16x16x32_bf16 v[76:79], v[160:163], v[210:213], v[76:79]
	v_mfma_f32_16x16x32_bf16 v[120:123], v[164:167], v[180:183], v[120:123]
	v_mfma_f32_16x16x32_bf16 v[116:119], v[172:175], v[180:183], v[116:119]
	v_mfma_f32_16x16x32_bf16 v[104:107], v[164:167], v[188:191], v[104:107]
	v_mfma_f32_16x16x32_bf16 v[100:103], v[172:175], v[188:191], v[100:103]
	v_mfma_f32_16x16x32_bf16 v[88:91], v[164:167], v[196:199], v[88:91]
	v_mfma_f32_16x16x32_bf16 v[84:87], v[172:175], v[196:199], v[84:87]
	v_mfma_f32_16x16x32_bf16 v[72:75], v[164:167], v[204:207], v[72:75]
	v_mfma_f32_16x16x32_bf16 v[68:71], v[172:175], v[204:207], v[68:71]
	v_mfma_f32_16x16x32_bf16 v[120:123], v[168:171], v[184:187], v[120:123]
	v_mfma_f32_16x16x32_bf16 v[116:119], v[176:179], v[184:187], v[116:119]
	v_mfma_f32_16x16x32_bf16 v[104:107], v[168:171], v[192:195], v[104:107]
	v_mfma_f32_16x16x32_bf16 v[100:103], v[176:179], v[192:195], v[100:103]
	v_mfma_f32_16x16x32_bf16 v[88:91], v[168:171], v[200:203], v[88:91]
	v_mfma_f32_16x16x32_bf16 v[84:87], v[176:179], v[200:203], v[84:87]
	v_mfma_f32_16x16x32_bf16 v[72:75], v[168:171], v[210:213], v[72:75]
	v_mfma_f32_16x16x32_bf16 v[68:71], v[176:179], v[210:213], v[68:71]
	s_barrier
	s_add_i32 s58, s61, s37
	v_lshl_add_u64 v[148:149], s[6:7], 0, v[136:137]
	s_mov_b32 m0, s58
	ds_read_b128 v[180:183], v151 offset:16384
	ds_read_b128 v[184:187], v151 offset:17408
	ds_read_b128 v[188:191], v151 offset:18432
	ds_read_b128 v[192:195], v151 offset:19456
	ds_read_b128 v[196:199], v151 offset:20480
	ds_read_b128 v[200:203], v151 offset:21504
	ds_read_b128 v[204:207], v151 offset:22528
	ds_read_b128 v[210:213], v151 offset:23552
	global_load_lds_dwordx4 v[148:149], off
	s_add_i32 m0, s58, 0x2000
	s_add_u32 s58, s6, 0x40000
	v_lshl_add_u64 v[218:219], s[6:7], 0, v[132:133]
	s_addc_u32 s59, s7, 0
	s_add_i32 s60, s77, s37
	global_load_lds_dwordx4 v[218:219], off
	v_lshl_add_u64 v[220:221], s[58:59], 0, v[136:137]
	s_mov_b32 m0, s60
	v_lshl_add_u64 v[222:223], s[8:9], 0, v[134:135]
	global_load_lds_dwordx4 v[220:221], off
	v_lshl_add_u64 v[220:221], s[58:59], 0, v[132:133]
	s_add_i32 m0, s60, 0x2000
	s_nop 0
	global_load_lds_dwordx4 v[220:221], off
	v_lshl_add_u64 v[220:221], s[8:9], 0, v[138:139]
	s_mov_b32 m0, s19
	s_nop 0
	global_load_lds_dwordx4 v[220:221], off
	s_mov_b32 m0, s39
	s_nop 0
	global_load_lds_dwordx4 v[222:223], off
	s_waitcnt vmcnt(8)
	s_waitcnt lgkmcnt(0)
	s_barrier
	s_waitcnt lgkmcnt(0)
	v_mfma_f32_16x16x32_bf16 v[64:67], v[144:147], v[180:183], v[64:67]
	v_mfma_f32_16x16x32_bf16 v[60:63], v[156:159], v[180:183], v[60:63]
	v_mfma_f32_16x16x32_bf16 v[48:51], v[144:147], v[188:191], v[48:51]
	v_mfma_f32_16x16x32_bf16 v[44:47], v[156:159], v[188:191], v[44:47]
	v_mfma_f32_16x16x32_bf16 v[32:35], v[144:147], v[196:199], v[32:35]
	v_mfma_f32_16x16x32_bf16 v[28:31], v[156:159], v[196:199], v[28:31]
	v_mfma_f32_16x16x32_bf16 v[16:19], v[144:147], v[204:207], v[16:19]
	v_mfma_f32_16x16x32_bf16 v[12:15], v[156:159], v[204:207], v[12:15]
	v_mfma_f32_16x16x32_bf16 v[64:67], v[152:155], v[184:187], v[64:67]
	v_mfma_f32_16x16x32_bf16 v[60:63], v[160:163], v[184:187], v[60:63]
	v_mfma_f32_16x16x32_bf16 v[48:51], v[152:155], v[192:195], v[48:51]
	v_mfma_f32_16x16x32_bf16 v[44:47], v[160:163], v[192:195], v[44:47]
	v_mfma_f32_16x16x32_bf16 v[32:35], v[152:155], v[200:203], v[32:35]
	v_mfma_f32_16x16x32_bf16 v[28:31], v[160:163], v[200:203], v[28:31]
	v_mfma_f32_16x16x32_bf16 v[16:19], v[152:155], v[210:213], v[16:19]
	v_mfma_f32_16x16x32_bf16 v[12:15], v[160:163], v[210:213], v[12:15]
	v_mfma_f32_16x16x32_bf16 v[56:59], v[164:167], v[180:183], v[56:59]
	v_mfma_f32_16x16x32_bf16 v[52:55], v[172:175], v[180:183], v[52:55]
	v_mfma_f32_16x16x32_bf16 v[40:43], v[164:167], v[188:191], v[40:43]
	v_mfma_f32_16x16x32_bf16 v[36:39], v[172:175], v[188:191], v[36:39]
	v_mfma_f32_16x16x32_bf16 v[24:27], v[164:167], v[196:199], v[24:27]
	v_mfma_f32_16x16x32_bf16 v[20:23], v[172:175], v[196:199], v[20:23]
	v_mfma_f32_16x16x32_bf16 v[8:11], v[164:167], v[204:207], v[8:11]
	v_mfma_f32_16x16x32_bf16 v[4:7], v[172:175], v[204:207], v[4:7]
	v_mfma_f32_16x16x32_bf16 v[56:59], v[168:171], v[184:187], v[56:59]
	v_mfma_f32_16x16x32_bf16 v[52:55], v[176:179], v[184:187], v[52:55]
	v_mfma_f32_16x16x32_bf16 v[40:43], v[168:171], v[192:195], v[40:43]
	v_mfma_f32_16x16x32_bf16 v[36:39], v[176:179], v[192:195], v[36:39]
	v_mfma_f32_16x16x32_bf16 v[24:27], v[168:171], v[200:203], v[24:27]
	v_mfma_f32_16x16x32_bf16 v[20:23], v[176:179], v[200:203], v[20:23]
	v_mfma_f32_16x16x32_bf16 v[8:11], v[168:171], v[210:213], v[8:11]
	v_mfma_f32_16x16x32_bf16 v[4:7], v[176:179], v[210:213], v[4:7]
	s_barrier
	v_add_u32_e32 v160, s79, v150
	v_add_u32_e32 v176, s80, v150
	ds_read_b128 v[144:147], v160
	ds_read_b128 v[152:155], v160 offset:1024
	ds_read_b128 v[156:159], v160 offset:2048
	ds_read_b128 v[160:163], v160 offset:3072
	ds_read_b128 v[164:167], v176
	ds_read_b128 v[168:171], v176 offset:1024
	ds_read_b128 v[172:175], v176 offset:2048
	ds_read_b128 v[176:179], v176 offset:3072
	s_add_u32 s8, s8, 0x100000
	s_addc_u32 s9, s9, 0
	s_mov_b32 m0, s40
	v_lshl_add_u64 v[224:225], s[8:9], 0, v[138:139]
	ds_read_b128 v[180:183], v151 offset:32768
	ds_read_b128 v[184:187], v151 offset:33792
	ds_read_b128 v[188:191], v151 offset:34816
	ds_read_b128 v[192:195], v151 offset:35840
	ds_read_b128 v[196:199], v151 offset:36864
	ds_read_b128 v[200:203], v151 offset:37888
	ds_read_b128 v[204:207], v151 offset:38912
	ds_read_b128 v[210:213], v151 offset:39936
	global_load_lds_dwordx4 v[224:225], off
	v_lshl_add_u64 v[224:225], s[8:9], 0, v[134:135]
	s_mov_b32 m0, s41
	s_nop 0
	global_load_lds_dwordx4 v[224:225], off
	s_waitcnt vmcnt(8)
	s_waitcnt lgkmcnt(0)
	s_barrier
	s_waitcnt lgkmcnt(0)
	v_mfma_f32_16x16x32_bf16 v[128:131], v[144:147], v[180:183], v[128:131]
	v_mfma_f32_16x16x32_bf16 v[124:127], v[156:159], v[180:183], v[124:127]
	v_mfma_f32_16x16x32_bf16 v[112:115], v[144:147], v[188:191], v[112:115]
	v_mfma_f32_16x16x32_bf16 v[108:111], v[156:159], v[188:191], v[108:111]
	v_mfma_f32_16x16x32_bf16 v[96:99], v[144:147], v[196:199], v[96:99]
	v_mfma_f32_16x16x32_bf16 v[92:95], v[156:159], v[196:199], v[92:95]
	v_mfma_f32_16x16x32_bf16 v[80:83], v[144:147], v[204:207], v[80:83]
	v_mfma_f32_16x16x32_bf16 v[76:79], v[156:159], v[204:207], v[76:79]
	v_mfma_f32_16x16x32_bf16 v[128:131], v[152:155], v[184:187], v[128:131]
	v_mfma_f32_16x16x32_bf16 v[124:127], v[160:163], v[184:187], v[124:127]
	v_mfma_f32_16x16x32_bf16 v[112:115], v[152:155], v[192:195], v[112:115]
	v_mfma_f32_16x16x32_bf16 v[108:111], v[160:163], v[192:195], v[108:111]
	v_mfma_f32_16x16x32_bf16 v[96:99], v[152:155], v[200:203], v[96:99]
	v_mfma_f32_16x16x32_bf16 v[92:95], v[160:163], v[200:203], v[92:95]
	v_mfma_f32_16x16x32_bf16 v[80:83], v[152:155], v[210:213], v[80:83]
	v_mfma_f32_16x16x32_bf16 v[76:79], v[160:163], v[210:213], v[76:79]
	v_mfma_f32_16x16x32_bf16 v[120:123], v[164:167], v[180:183], v[120:123]
	v_mfma_f32_16x16x32_bf16 v[116:119], v[172:175], v[180:183], v[116:119]
	v_mfma_f32_16x16x32_bf16 v[104:107], v[164:167], v[188:191], v[104:107]
	v_mfma_f32_16x16x32_bf16 v[100:103], v[172:175], v[188:191], v[100:103]
	v_mfma_f32_16x16x32_bf16 v[88:91], v[164:167], v[196:199], v[88:91]
	v_mfma_f32_16x16x32_bf16 v[84:87], v[172:175], v[196:199], v[84:87]
	v_mfma_f32_16x16x32_bf16 v[72:75], v[164:167], v[204:207], v[72:75]
	v_mfma_f32_16x16x32_bf16 v[68:71], v[172:175], v[204:207], v[68:71]
	v_mfma_f32_16x16x32_bf16 v[120:123], v[168:171], v[184:187], v[120:123]
	v_mfma_f32_16x16x32_bf16 v[116:119], v[176:179], v[184:187], v[116:119]
	v_mfma_f32_16x16x32_bf16 v[104:107], v[168:171], v[192:195], v[104:107]
	v_mfma_f32_16x16x32_bf16 v[100:103], v[176:179], v[192:195], v[100:103]
	v_mfma_f32_16x16x32_bf16 v[88:91], v[168:171], v[200:203], v[88:91]
	v_mfma_f32_16x16x32_bf16 v[84:87], v[176:179], v[200:203], v[84:87]
	v_mfma_f32_16x16x32_bf16 v[72:75], v[168:171], v[210:213], v[72:75]
	v_mfma_f32_16x16x32_bf16 v[68:71], v[176:179], v[210:213], v[68:71]
	s_barrier
	s_add_i32 s8, s79, s37
	v_lshl_add_u64 v[148:149], v[148:149], 0, s[56:57]
	s_mov_b32 m0, s8
	ds_read_b128 v[180:183], v151 offset:49152
	ds_read_b128 v[184:187], v151 offset:50176
	ds_read_b128 v[188:191], v151 offset:51200
	ds_read_b128 v[192:195], v151 offset:52224
	ds_read_b128 v[196:199], v151 offset:53248
	ds_read_b128 v[200:203], v151 offset:54272
	ds_read_b128 v[204:207], v151 offset:55296
	ds_read_b128 v[210:213], v151 offset:56320
	global_load_lds_dwordx4 v[148:149], off
	s_add_i32 m0, s8, 0x2000
	s_add_u32 s6, s6, 0x40080
	v_lshl_add_u64 v[148:149], v[218:219], 0, s[56:57]
	s_addc_u32 s7, s7, 0
	s_add_i32 s8, s80, s37
	global_load_lds_dwordx4 v[148:149], off
	v_lshl_add_u64 v[148:149], s[6:7], 0, v[136:137]
	s_mov_b32 m0, s8
	s_nop 0
	global_load_lds_dwordx4 v[148:149], off
	v_lshl_add_u64 v[148:149], s[6:7], 0, v[132:133]
	s_add_i32 m0, s8, 0x2000
	s_nop 0
	global_load_lds_dwordx4 v[148:149], off
	v_lshl_add_u64 v[148:149], v[220:221], 0, s[56:57]
	s_mov_b32 m0, s43
	s_nop 0
	global_load_lds_dwordx4 v[148:149], off
	v_lshl_add_u64 v[148:149], v[222:223], 0, s[56:57]
	s_mov_b32 m0, s44
	s_nop 0
	global_load_lds_dwordx4 v[148:149], off
	s_waitcnt vmcnt(8)
	s_waitcnt lgkmcnt(0)
	s_barrier
	s_waitcnt lgkmcnt(0)
	v_mfma_f32_16x16x32_bf16 v[64:67], v[144:147], v[180:183], v[64:67]
	v_mfma_f32_16x16x32_bf16 v[60:63], v[156:159], v[180:183], v[60:63]
	v_mfma_f32_16x16x32_bf16 v[48:51], v[144:147], v[188:191], v[48:51]
	v_mfma_f32_16x16x32_bf16 v[44:47], v[156:159], v[188:191], v[44:47]
	v_mfma_f32_16x16x32_bf16 v[32:35], v[144:147], v[196:199], v[32:35]
	v_mfma_f32_16x16x32_bf16 v[28:31], v[156:159], v[196:199], v[28:31]
	v_mfma_f32_16x16x32_bf16 v[16:19], v[144:147], v[204:207], v[16:19]
	v_mfma_f32_16x16x32_bf16 v[12:15], v[156:159], v[204:207], v[12:15]
	v_mfma_f32_16x16x32_bf16 v[64:67], v[152:155], v[184:187], v[64:67]
	v_mfma_f32_16x16x32_bf16 v[60:63], v[160:163], v[184:187], v[60:63]
	v_mfma_f32_16x16x32_bf16 v[48:51], v[152:155], v[192:195], v[48:51]
	v_mfma_f32_16x16x32_bf16 v[44:47], v[160:163], v[192:195], v[44:47]
	v_mfma_f32_16x16x32_bf16 v[32:35], v[152:155], v[200:203], v[32:35]
	v_mfma_f32_16x16x32_bf16 v[28:31], v[160:163], v[200:203], v[28:31]
	v_mfma_f32_16x16x32_bf16 v[16:19], v[152:155], v[210:213], v[16:19]
	v_mfma_f32_16x16x32_bf16 v[12:15], v[160:163], v[210:213], v[12:15]
	v_mfma_f32_16x16x32_bf16 v[56:59], v[164:167], v[180:183], v[56:59]
	v_mfma_f32_16x16x32_bf16 v[52:55], v[172:175], v[180:183], v[52:55]
	v_mfma_f32_16x16x32_bf16 v[40:43], v[164:167], v[188:191], v[40:43]
	v_mfma_f32_16x16x32_bf16 v[36:39], v[172:175], v[188:191], v[36:39]
	v_mfma_f32_16x16x32_bf16 v[24:27], v[164:167], v[196:199], v[24:27]
	v_mfma_f32_16x16x32_bf16 v[20:23], v[172:175], v[196:199], v[20:23]
	v_mfma_f32_16x16x32_bf16 v[8:11], v[164:167], v[204:207], v[8:11]
	v_mfma_f32_16x16x32_bf16 v[4:7], v[172:175], v[204:207], v[4:7]
	v_mfma_f32_16x16x32_bf16 v[56:59], v[168:171], v[184:187], v[56:59]
	v_mfma_f32_16x16x32_bf16 v[52:55], v[176:179], v[184:187], v[52:55]
	v_mfma_f32_16x16x32_bf16 v[40:43], v[168:171], v[192:195], v[40:43]
	v_mfma_f32_16x16x32_bf16 v[36:39], v[176:179], v[192:195], v[36:39]
	v_mfma_f32_16x16x32_bf16 v[24:27], v[168:171], v[200:203], v[24:27]
	v_mfma_f32_16x16x32_bf16 v[20:23], v[176:179], v[200:203], v[20:23]
	v_mfma_f32_16x16x32_bf16 v[8:11], v[168:171], v[210:213], v[8:11]
	v_mfma_f32_16x16x32_bf16 v[4:7], v[176:179], v[210:213], v[4:7]
	s_barrier
	s_add_i32 s53, s53, 2
	s_add_u32 s4, s4, 0x100
	s_addc_u32 s5, s5, 0
	s_add_u32 s29, s29, 0x100
	s_addc_u32 s52, s52, 0
	s_cmp_gt_u32 s53, 13
	s_cbranch_scc0 .LBB0_2100
	s_and_b64 vcc, exec, s[26:27]
	s_cbranch_vccz .LBB0_2103
	s_barrier

.LBB0_2189:
	v_add_u32_e32 v2, s61, v151
	ds_read_b128 v[144:147], v2
	ds_read_b128 v[154:157], v2 offset:1024
	ds_read_b128 v[158:161], v2 offset:2048
	ds_read_b128 v[162:165], v2 offset:3072
	v_add_u32_e32 v2, s77, v151
	ds_read_b128 v[166:169], v2
	ds_read_b128 v[170:173], v2 offset:1024
	ds_read_b128 v[174:177], v2 offset:2048
	ds_read_b128 v[178:181], v2 offset:3072
	s_add_u32 s26, s4, 0xfffc0080
	s_addc_u32 s27, s5, -1
	s_cmp_eq_u32 s53, 12
	s_cselect_b32 s29, s25, s27
	s_cselect_b32 s28, s49, s26
	s_cselect_b32 s27, s23, s52
	s_cselect_b32 s26, s50, s51
	v_lshl_add_u64 v[148:149], s[4:5], 0, v[140:141]
	s_add_i32 m0, s13, 0xc000
	ds_read_b128 v[182:185], v152
	ds_read_b128 v[186:189], v152 offset:1024
	ds_read_b128 v[190:193], v152 offset:2048
	ds_read_b128 v[194:197], v152 offset:3072
	ds_read_b128 v[198:201], v152 offset:4096
	ds_read_b128 v[202:205], v152 offset:5120
	ds_read_b128 v[210:213], v152 offset:6144
	ds_read_b128 v[218:221], v152 offset:7168
	global_load_lds_dwordx4 v[148:149], off
	v_lshl_add_u64 v[148:149], s[4:5], 0, v[142:143]
	s_add_i32 m0, s13, 0xe000
	s_nop 0
	global_load_lds_dwordx4 v[148:149], off
	s_waitcnt vmcnt(8)
	s_waitcnt lgkmcnt(0)
	s_barrier
	s_waitcnt lgkmcnt(0)
	v_mfma_f32_16x16x32_bf16 v[128:131], v[144:147], v[182:185], v[128:131]
	v_mfma_f32_16x16x32_bf16 v[124:127], v[158:161], v[182:185], v[124:127]
	v_mfma_f32_16x16x32_bf16 v[112:115], v[144:147], v[190:193], v[112:115]
	v_mfma_f32_16x16x32_bf16 v[108:111], v[158:161], v[190:193], v[108:111]
	v_mfma_f32_16x16x32_bf16 v[96:99], v[144:147], v[198:201], v[96:99]
	v_mfma_f32_16x16x32_bf16 v[92:95], v[158:161], v[198:201], v[92:95]
	v_mfma_f32_16x16x32_bf16 v[80:83], v[144:147], v[210:213], v[80:83]
	v_mfma_f32_16x16x32_bf16 v[76:79], v[158:161], v[210:213], v[76:79]
	v_mfma_f32_16x16x32_bf16 v[128:131], v[154:157], v[186:189], v[128:131]
	v_mfma_f32_16x16x32_bf16 v[124:127], v[162:165], v[186:189], v[124:127]
	v_mfma_f32_16x16x32_bf16 v[112:115], v[154:157], v[194:197], v[112:115]
	v_mfma_f32_16x16x32_bf16 v[108:111], v[162:165], v[194:197], v[108:111]
	v_mfma_f32_16x16x32_bf16 v[96:99], v[154:157], v[202:205], v[96:99]
	v_mfma_f32_16x16x32_bf16 v[92:95], v[162:165], v[202:205], v[92:95]
	v_mfma_f32_16x16x32_bf16 v[80:83], v[154:157], v[218:221], v[80:83]
	v_mfma_f32_16x16x32_bf16 v[76:79], v[162:165], v[218:221], v[76:79]
	v_mfma_f32_16x16x32_bf16 v[120:123], v[166:169], v[182:185], v[120:123]
	v_mfma_f32_16x16x32_bf16 v[116:119], v[174:177], v[182:185], v[116:119]
	v_mfma_f32_16x16x32_bf16 v[104:107], v[166:169], v[190:193], v[104:107]
	v_mfma_f32_16x16x32_bf16 v[100:103], v[174:177], v[190:193], v[100:103]
	v_mfma_f32_16x16x32_bf16 v[88:91], v[166:169], v[198:201], v[88:91]
	v_mfma_f32_16x16x32_bf16 v[84:87], v[174:177], v[198:201], v[84:87]
	v_mfma_f32_16x16x32_bf16 v[72:75], v[166:169], v[210:213], v[72:75]
	v_mfma_f32_16x16x32_bf16 v[68:71], v[174:177], v[210:213], v[68:71]
	v_mfma_f32_16x16x32_bf16 v[120:123], v[170:173], v[186:189], v[120:123]
	v_mfma_f32_16x16x32_bf16 v[116:119], v[178:181], v[186:189], v[116:119]
	v_mfma_f32_16x16x32_bf16 v[104:107], v[170:173], v[194:197], v[104:107]
	v_mfma_f32_16x16x32_bf16 v[100:103], v[178:181], v[194:197], v[100:103]
	v_mfma_f32_16x16x32_bf16 v[88:91], v[170:173], v[202:205], v[88:91]
	v_mfma_f32_16x16x32_bf16 v[84:87], v[178:181], v[202:205], v[84:87]
	v_mfma_f32_16x16x32_bf16 v[72:75], v[170:173], v[218:221], v[72:75]
	v_mfma_f32_16x16x32_bf16 v[68:71], v[178:181], v[218:221], v[68:71]
	s_barrier
	s_add_i32 s58, s61, s35
	v_lshl_add_u64 v[148:149], s[26:27], 0, v[136:137]
	s_mov_b32 m0, s58
	ds_read_b128 v[182:185], v152 offset:16384
	ds_read_b128 v[186:189], v152 offset:17408
	ds_read_b128 v[190:193], v152 offset:18432
	ds_read_b128 v[194:197], v152 offset:19456
	ds_read_b128 v[198:201], v152 offset:20480
	ds_read_b128 v[202:205], v152 offset:21504
	ds_read_b128 v[210:213], v152 offset:22528
	ds_read_b128 v[218:221], v152 offset:23552
	global_load_lds_dwordx4 v[148:149], off
	s_add_i32 m0, s58, 0x2000
	s_add_u32 s58, s26, 0x40000
	v_lshl_add_u64 v[206:207], s[26:27], 0, v[132:133]
	s_addc_u32 s59, s27, 0
	s_add_i32 s60, s77, s35
	global_load_lds_dwordx4 v[206:207], off
	v_lshl_add_u64 v[222:223], s[58:59], 0, v[136:137]
	s_mov_b32 m0, s60
	v_lshl_add_u64 v[224:225], s[28:29], 0, v[134:135]
	global_load_lds_dwordx4 v[222:223], off
	v_lshl_add_u64 v[222:223], s[58:59], 0, v[132:133]
	s_add_i32 m0, s60, 0x2000
	s_nop 0
	global_load_lds_dwordx4 v[222:223], off
	v_lshl_add_u64 v[222:223], s[28:29], 0, v[138:139]
	s_mov_b32 m0, s13
	s_nop 0
	global_load_lds_dwordx4 v[222:223], off
	s_mov_b32 m0, s37
	s_nop 0
	global_load_lds_dwordx4 v[224:225], off
	s_waitcnt vmcnt(8)
	s_waitcnt lgkmcnt(0)
	s_barrier
	s_waitcnt lgkmcnt(0)
	v_mfma_f32_16x16x32_bf16 v[64:67], v[144:147], v[182:185], v[64:67]
	v_mfma_f32_16x16x32_bf16 v[60:63], v[158:161], v[182:185], v[60:63]
	v_mfma_f32_16x16x32_bf16 v[48:51], v[144:147], v[190:193], v[48:51]
	v_mfma_f32_16x16x32_bf16 v[44:47], v[158:161], v[190:193], v[44:47]
	v_mfma_f32_16x16x32_bf16 v[32:35], v[144:147], v[198:201], v[32:35]
	v_mfma_f32_16x16x32_bf16 v[28:31], v[158:161], v[198:201], v[28:31]
	v_mfma_f32_16x16x32_bf16 v[16:19], v[144:147], v[210:213], v[16:19]
	v_mfma_f32_16x16x32_bf16 v[12:15], v[158:161], v[210:213], v[12:15]
	v_mfma_f32_16x16x32_bf16 v[64:67], v[154:157], v[186:189], v[64:67]
	v_mfma_f32_16x16x32_bf16 v[60:63], v[162:165], v[186:189], v[60:63]
	v_mfma_f32_16x16x32_bf16 v[48:51], v[154:157], v[194:197], v[48:51]
	v_mfma_f32_16x16x32_bf16 v[44:47], v[162:165], v[194:197], v[44:47]
	v_mfma_f32_16x16x32_bf16 v[32:35], v[154:157], v[202:205], v[32:35]
	v_mfma_f32_16x16x32_bf16 v[28:31], v[162:165], v[202:205], v[28:31]
	v_mfma_f32_16x16x32_bf16 v[16:19], v[154:157], v[218:221], v[16:19]
	v_mfma_f32_16x16x32_bf16 v[12:15], v[162:165], v[218:221], v[12:15]
	v_mfma_f32_16x16x32_bf16 v[56:59], v[166:169], v[182:185], v[56:59]
	v_mfma_f32_16x16x32_bf16 v[52:55], v[174:177], v[182:185], v[52:55]
	v_mfma_f32_16x16x32_bf16 v[40:43], v[166:169], v[190:193], v[40:43]
	v_mfma_f32_16x16x32_bf16 v[36:39], v[174:177], v[190:193], v[36:39]
	v_mfma_f32_16x16x32_bf16 v[24:27], v[166:169], v[198:201], v[24:27]
	v_mfma_f32_16x16x32_bf16 v[20:23], v[174:177], v[198:201], v[20:23]
	v_mfma_f32_16x16x32_bf16 v[8:11], v[166:169], v[210:213], v[8:11]
	v_mfma_f32_16x16x32_bf16 v[4:7], v[174:177], v[210:213], v[4:7]
	v_mfma_f32_16x16x32_bf16 v[56:59], v[170:173], v[186:189], v[56:59]
	v_mfma_f32_16x16x32_bf16 v[52:55], v[178:181], v[186:189], v[52:55]
	v_mfma_f32_16x16x32_bf16 v[40:43], v[170:173], v[194:197], v[40:43]
	v_mfma_f32_16x16x32_bf16 v[36:39], v[178:181], v[194:197], v[36:39]
	v_mfma_f32_16x16x32_bf16 v[24:27], v[170:173], v[202:205], v[24:27]
	v_mfma_f32_16x16x32_bf16 v[20:23], v[178:181], v[202:205], v[20:23]
	v_mfma_f32_16x16x32_bf16 v[8:11], v[170:173], v[218:221], v[8:11]
	v_mfma_f32_16x16x32_bf16 v[4:7], v[178:181], v[218:221], v[4:7]
	s_barrier
	v_add_u32_e32 v2, s79, v151
	ds_read_b128 v[144:147], v2
	ds_read_b128 v[154:157], v2 offset:1024
	ds_read_b128 v[158:161], v2 offset:2048
	ds_read_b128 v[162:165], v2 offset:3072
	v_add_u32_e32 v2, s80, v151
	ds_read_b128 v[166:169], v2
	ds_read_b128 v[170:173], v2 offset:1024
	ds_read_b128 v[174:177], v2 offset:2048
	ds_read_b128 v[178:181], v2 offset:3072
	s_add_u32 s28, s28, 0x40000
	s_addc_u32 s29, s29, 0
	s_mov_b32 m0, s38
	v_lshl_add_u64 v[226:227], s[28:29], 0, v[138:139]
	ds_read_b128 v[182:185], v152 offset:32768
	ds_read_b128 v[186:189], v152 offset:33792
	ds_read_b128 v[190:193], v152 offset:34816
	ds_read_b128 v[194:197], v152 offset:35840
	ds_read_b128 v[198:201], v152 offset:36864
	ds_read_b128 v[202:205], v152 offset:37888
	ds_read_b128 v[210:213], v152 offset:38912
	ds_read_b128 v[218:221], v152 offset:39936
	global_load_lds_dwordx4 v[226:227], off
	v_lshl_add_u64 v[226:227], s[28:29], 0, v[134:135]
	s_mov_b32 m0, s39
	s_nop 0
	global_load_lds_dwordx4 v[226:227], off
	s_waitcnt vmcnt(8)
	s_waitcnt lgkmcnt(0)
	s_barrier
	s_waitcnt lgkmcnt(0)
	v_mfma_f32_16x16x32_bf16 v[128:131], v[144:147], v[182:185], v[128:131]
	v_mfma_f32_16x16x32_bf16 v[124:127], v[158:161], v[182:185], v[124:127]
	v_mfma_f32_16x16x32_bf16 v[112:115], v[144:147], v[190:193], v[112:115]
	v_mfma_f32_16x16x32_bf16 v[108:111], v[158:161], v[190:193], v[108:111]
	v_mfma_f32_16x16x32_bf16 v[96:99], v[144:147], v[198:201], v[96:99]
	v_mfma_f32_16x16x32_bf16 v[92:95], v[158:161], v[198:201], v[92:95]
	v_mfma_f32_16x16x32_bf16 v[80:83], v[144:147], v[210:213], v[80:83]
	v_mfma_f32_16x16x32_bf16 v[76:79], v[158:161], v[210:213], v[76:79]
	v_mfma_f32_16x16x32_bf16 v[128:131], v[154:157], v[186:189], v[128:131]
	v_mfma_f32_16x16x32_bf16 v[124:127], v[162:165], v[186:189], v[124:127]
	v_mfma_f32_16x16x32_bf16 v[112:115], v[154:157], v[194:197], v[112:115]
	v_mfma_f32_16x16x32_bf16 v[108:111], v[162:165], v[194:197], v[108:111]
	v_mfma_f32_16x16x32_bf16 v[96:99], v[154:157], v[202:205], v[96:99]
	v_mfma_f32_16x16x32_bf16 v[92:95], v[162:165], v[202:205], v[92:95]
	v_mfma_f32_16x16x32_bf16 v[80:83], v[154:157], v[218:221], v[80:83]
	v_mfma_f32_16x16x32_bf16 v[76:79], v[162:165], v[218:221], v[76:79]
	v_mfma_f32_16x16x32_bf16 v[120:123], v[166:169], v[182:185], v[120:123]
	v_mfma_f32_16x16x32_bf16 v[116:119], v[174:177], v[182:185], v[116:119]
	v_mfma_f32_16x16x32_bf16 v[104:107], v[166:169], v[190:193], v[104:107]
	v_mfma_f32_16x16x32_bf16 v[100:103], v[174:177], v[190:193], v[100:103]
	v_mfma_f32_16x16x32_bf16 v[88:91], v[166:169], v[198:201], v[88:91]
	v_mfma_f32_16x16x32_bf16 v[84:87], v[174:177], v[198:201], v[84:87]
	v_mfma_f32_16x16x32_bf16 v[72:75], v[166:169], v[210:213], v[72:75]
	v_mfma_f32_16x16x32_bf16 v[68:71], v[174:177], v[210:213], v[68:71]
	v_mfma_f32_16x16x32_bf16 v[120:123], v[170:173], v[186:189], v[120:123]
	v_mfma_f32_16x16x32_bf16 v[116:119], v[178:181], v[186:189], v[116:119]
	v_mfma_f32_16x16x32_bf16 v[104:107], v[170:173], v[194:197], v[104:107]
	v_mfma_f32_16x16x32_bf16 v[100:103], v[178:181], v[194:197], v[100:103]
	v_mfma_f32_16x16x32_bf16 v[88:91], v[170:173], v[202:205], v[88:91]
	v_mfma_f32_16x16x32_bf16 v[84:87], v[178:181], v[202:205], v[84:87]
	v_mfma_f32_16x16x32_bf16 v[72:75], v[170:173], v[218:221], v[72:75]
	v_mfma_f32_16x16x32_bf16 v[68:71], v[178:181], v[218:221], v[68:71]
	s_barrier
	s_add_i32 s28, s79, s35
	v_lshl_add_u64 v[148:149], v[148:149], 0, s[56:57]
	s_mov_b32 m0, s28
	ds_read_b128 v[182:185], v152 offset:49152
	ds_read_b128 v[186:189], v152 offset:50176
	ds_read_b128 v[190:193], v152 offset:51200
	ds_read_b128 v[194:197], v152 offset:52224
	ds_read_b128 v[198:201], v152 offset:53248
	ds_read_b128 v[202:205], v152 offset:54272
	ds_read_b128 v[210:213], v152 offset:55296
	ds_read_b128 v[218:221], v152 offset:56320
	global_load_lds_dwordx4 v[148:149], off
	s_add_i32 m0, s28, 0x2000
	s_add_u32 s26, s26, 0x40080
	v_lshl_add_u64 v[148:149], v[206:207], 0, s[56:57]
	s_addc_u32 s27, s27, 0
	s_add_i32 s28, s80, s35
	global_load_lds_dwordx4 v[148:149], off
	v_lshl_add_u64 v[148:149], s[26:27], 0, v[136:137]
	s_mov_b32 m0, s28
	s_nop 0
	global_load_lds_dwordx4 v[148:149], off
	v_lshl_add_u64 v[148:149], s[26:27], 0, v[132:133]
	s_add_i32 m0, s28, 0x2000
	s_nop 0
	global_load_lds_dwordx4 v[148:149], off
	v_lshl_add_u64 v[148:149], v[222:223], 0, s[56:57]
	s_mov_b32 m0, s41
	s_nop 0
	global_load_lds_dwordx4 v[148:149], off
	v_lshl_add_u64 v[148:149], v[224:225], 0, s[56:57]
	s_mov_b32 m0, s42
	s_nop 0
	global_load_lds_dwordx4 v[148:149], off
	s_waitcnt vmcnt(8)
	s_waitcnt lgkmcnt(0)
	s_barrier
	s_waitcnt lgkmcnt(0)
	v_mfma_f32_16x16x32_bf16 v[64:67], v[144:147], v[182:185], v[64:67]
	v_mfma_f32_16x16x32_bf16 v[60:63], v[158:161], v[182:185], v[60:63]
	v_mfma_f32_16x16x32_bf16 v[48:51], v[144:147], v[190:193], v[48:51]
	v_mfma_f32_16x16x32_bf16 v[44:47], v[158:161], v[190:193], v[44:47]
	v_mfma_f32_16x16x32_bf16 v[32:35], v[144:147], v[198:201], v[32:35]
	v_mfma_f32_16x16x32_bf16 v[28:31], v[158:161], v[198:201], v[28:31]
	v_mfma_f32_16x16x32_bf16 v[16:19], v[144:147], v[210:213], v[16:19]
	v_mfma_f32_16x16x32_bf16 v[12:15], v[158:161], v[210:213], v[12:15]
	v_mfma_f32_16x16x32_bf16 v[64:67], v[154:157], v[186:189], v[64:67]
	v_mfma_f32_16x16x32_bf16 v[60:63], v[162:165], v[186:189], v[60:63]
	v_mfma_f32_16x16x32_bf16 v[48:51], v[154:157], v[194:197], v[48:51]
	v_mfma_f32_16x16x32_bf16 v[44:47], v[162:165], v[194:197], v[44:47]
	v_mfma_f32_16x16x32_bf16 v[32:35], v[154:157], v[202:205], v[32:35]
	v_mfma_f32_16x16x32_bf16 v[28:31], v[162:165], v[202:205], v[28:31]
	v_mfma_f32_16x16x32_bf16 v[16:19], v[154:157], v[218:221], v[16:19]
	v_mfma_f32_16x16x32_bf16 v[12:15], v[162:165], v[218:221], v[12:15]
	v_mfma_f32_16x16x32_bf16 v[56:59], v[166:169], v[182:185], v[56:59]
	v_mfma_f32_16x16x32_bf16 v[52:55], v[174:177], v[182:185], v[52:55]
	v_mfma_f32_16x16x32_bf16 v[40:43], v[166:169], v[190:193], v[40:43]
	v_mfma_f32_16x16x32_bf16 v[36:39], v[174:177], v[190:193], v[36:39]
	v_mfma_f32_16x16x32_bf16 v[24:27], v[166:169], v[198:201], v[24:27]
	v_mfma_f32_16x16x32_bf16 v[20:23], v[174:177], v[198:201], v[20:23]
	v_mfma_f32_16x16x32_bf16 v[8:11], v[166:169], v[210:213], v[8:11]
	v_mfma_f32_16x16x32_bf16 v[4:7], v[174:177], v[210:213], v[4:7]
	v_mfma_f32_16x16x32_bf16 v[56:59], v[170:173], v[186:189], v[56:59]
	v_mfma_f32_16x16x32_bf16 v[52:55], v[178:181], v[186:189], v[52:55]
	v_mfma_f32_16x16x32_bf16 v[40:43], v[170:173], v[194:197], v[40:43]
	v_mfma_f32_16x16x32_bf16 v[36:39], v[178:181], v[194:197], v[36:39]
	v_mfma_f32_16x16x32_bf16 v[24:27], v[170:173], v[202:205], v[24:27]
	v_mfma_f32_16x16x32_bf16 v[20:23], v[178:181], v[202:205], v[20:23]
	v_mfma_f32_16x16x32_bf16 v[8:11], v[170:173], v[218:221], v[8:11]
	v_mfma_f32_16x16x32_bf16 v[4:7], v[178:181], v[218:221], v[4:7]
	s_barrier
	s_add_i32 s53, s53, 2
	s_add_u32 s4, s4, 0x100
	s_addc_u32 s5, s5, 0
	s_add_u32 s51, s51, 0x100
	s_addc_u32 s52, s52, 0
	s_cmp_gt_u32 s53, 13
	s_cbranch_scc0 .LBB0_2189
	s_and_b64 vcc, exec, s[20:21]
	s_cbranch_vccz .LBB0_2192
	s_barrier

.LBB0_2540:
	v_add_u32_e32 v2, s61, v151
	ds_read_b128 v[144:147], v2
	ds_read_b128 v[154:157], v2 offset:1024
	ds_read_b128 v[158:161], v2 offset:2048
	ds_read_b128 v[162:165], v2 offset:3072
	v_add_u32_e32 v2, s77, v151
	ds_read_b128 v[166:169], v2
	ds_read_b128 v[170:173], v2 offset:1024
	ds_read_b128 v[174:177], v2 offset:2048
	ds_read_b128 v[178:181], v2 offset:3072
	s_add_u32 s26, s4, 0xfffc0080
	s_addc_u32 s27, s5, -1
	s_cmp_eq_u32 s53, 12
	s_cselect_b32 s29, s19, s27
	s_cselect_b32 s28, s49, s26
	s_cselect_b32 s27, s21, s52
	s_cselect_b32 s26, s50, s51
	v_lshl_add_u64 v[148:149], s[4:5], 0, v[140:141]
	s_add_i32 m0, s13, 0xc000
	ds_read_b128 v[182:185], v152
	ds_read_b128 v[186:189], v152 offset:1024
	ds_read_b128 v[190:193], v152 offset:2048
	ds_read_b128 v[194:197], v152 offset:3072
	ds_read_b128 v[198:201], v152 offset:4096
	ds_read_b128 v[202:205], v152 offset:5120
	ds_read_b128 v[210:213], v152 offset:6144
	ds_read_b128 v[218:221], v152 offset:7168
	global_load_lds_dwordx4 v[148:149], off
	v_lshl_add_u64 v[148:149], s[4:5], 0, v[142:143]
	s_add_i32 m0, s13, 0xe000
	s_nop 0
	global_load_lds_dwordx4 v[148:149], off
	s_waitcnt vmcnt(8)
	s_waitcnt lgkmcnt(0)
	s_barrier
	s_waitcnt lgkmcnt(0)
	v_mfma_f32_16x16x32_bf16 v[128:131], v[144:147], v[182:185], v[128:131]
	v_mfma_f32_16x16x32_bf16 v[124:127], v[158:161], v[182:185], v[124:127]
	v_mfma_f32_16x16x32_bf16 v[112:115], v[144:147], v[190:193], v[112:115]
	v_mfma_f32_16x16x32_bf16 v[108:111], v[158:161], v[190:193], v[108:111]
	v_mfma_f32_16x16x32_bf16 v[96:99], v[144:147], v[198:201], v[96:99]
	v_mfma_f32_16x16x32_bf16 v[92:95], v[158:161], v[198:201], v[92:95]
	v_mfma_f32_16x16x32_bf16 v[80:83], v[144:147], v[210:213], v[80:83]
	v_mfma_f32_16x16x32_bf16 v[76:79], v[158:161], v[210:213], v[76:79]
	v_mfma_f32_16x16x32_bf16 v[128:131], v[154:157], v[186:189], v[128:131]
	v_mfma_f32_16x16x32_bf16 v[124:127], v[162:165], v[186:189], v[124:127]
	v_mfma_f32_16x16x32_bf16 v[112:115], v[154:157], v[194:197], v[112:115]
	v_mfma_f32_16x16x32_bf16 v[108:111], v[162:165], v[194:197], v[108:111]
	v_mfma_f32_16x16x32_bf16 v[96:99], v[154:157], v[202:205], v[96:99]
	v_mfma_f32_16x16x32_bf16 v[92:95], v[162:165], v[202:205], v[92:95]
	v_mfma_f32_16x16x32_bf16 v[80:83], v[154:157], v[218:221], v[80:83]
	v_mfma_f32_16x16x32_bf16 v[76:79], v[162:165], v[218:221], v[76:79]
	v_mfma_f32_16x16x32_bf16 v[120:123], v[166:169], v[182:185], v[120:123]
	v_mfma_f32_16x16x32_bf16 v[116:119], v[174:177], v[182:185], v[116:119]
	v_mfma_f32_16x16x32_bf16 v[104:107], v[166:169], v[190:193], v[104:107]
	v_mfma_f32_16x16x32_bf16 v[100:103], v[174:177], v[190:193], v[100:103]
	v_mfma_f32_16x16x32_bf16 v[88:91], v[166:169], v[198:201], v[88:91]
	v_mfma_f32_16x16x32_bf16 v[84:87], v[174:177], v[198:201], v[84:87]
	v_mfma_f32_16x16x32_bf16 v[72:75], v[166:169], v[210:213], v[72:75]
	v_mfma_f32_16x16x32_bf16 v[68:71], v[174:177], v[210:213], v[68:71]
	v_mfma_f32_16x16x32_bf16 v[120:123], v[170:173], v[186:189], v[120:123]
	v_mfma_f32_16x16x32_bf16 v[116:119], v[178:181], v[186:189], v[116:119]
	v_mfma_f32_16x16x32_bf16 v[104:107], v[170:173], v[194:197], v[104:107]
	v_mfma_f32_16x16x32_bf16 v[100:103], v[178:181], v[194:197], v[100:103]
	v_mfma_f32_16x16x32_bf16 v[88:91], v[170:173], v[202:205], v[88:91]
	v_mfma_f32_16x16x32_bf16 v[84:87], v[178:181], v[202:205], v[84:87]
	v_mfma_f32_16x16x32_bf16 v[72:75], v[170:173], v[218:221], v[72:75]
	v_mfma_f32_16x16x32_bf16 v[68:71], v[178:181], v[218:221], v[68:71]
	s_barrier
	s_add_i32 s58, s61, s35
	v_lshl_add_u64 v[148:149], s[26:27], 0, v[136:137]
	s_mov_b32 m0, s58
	ds_read_b128 v[182:185], v152 offset:16384
	ds_read_b128 v[186:189], v152 offset:17408
	ds_read_b128 v[190:193], v152 offset:18432
	ds_read_b128 v[194:197], v152 offset:19456
	ds_read_b128 v[198:201], v152 offset:20480
	ds_read_b128 v[202:205], v152 offset:21504
	ds_read_b128 v[210:213], v152 offset:22528
	ds_read_b128 v[218:221], v152 offset:23552
	global_load_lds_dwordx4 v[148:149], off
	s_add_i32 m0, s58, 0x2000
	s_add_u32 s58, s26, 0x40000
	v_lshl_add_u64 v[206:207], s[26:27], 0, v[132:133]
	s_addc_u32 s59, s27, 0
	s_add_i32 s60, s77, s35
	global_load_lds_dwordx4 v[206:207], off
	v_lshl_add_u64 v[222:223], s[58:59], 0, v[136:137]
	s_mov_b32 m0, s60
	v_lshl_add_u64 v[224:225], s[28:29], 0, v[134:135]
	global_load_lds_dwordx4 v[222:223], off
	v_lshl_add_u64 v[222:223], s[58:59], 0, v[132:133]
	s_add_i32 m0, s60, 0x2000
	s_nop 0
	global_load_lds_dwordx4 v[222:223], off
	v_lshl_add_u64 v[222:223], s[28:29], 0, v[138:139]
	s_mov_b32 m0, s13
	s_nop 0
	global_load_lds_dwordx4 v[222:223], off
	s_mov_b32 m0, s36
	s_nop 0
	global_load_lds_dwordx4 v[224:225], off
	s_waitcnt vmcnt(8)
	s_waitcnt lgkmcnt(0)
	s_barrier
	s_waitcnt lgkmcnt(0)
	v_mfma_f32_16x16x32_bf16 v[64:67], v[144:147], v[182:185], v[64:67]
	v_mfma_f32_16x16x32_bf16 v[60:63], v[158:161], v[182:185], v[60:63]
	v_mfma_f32_16x16x32_bf16 v[48:51], v[144:147], v[190:193], v[48:51]
	v_mfma_f32_16x16x32_bf16 v[44:47], v[158:161], v[190:193], v[44:47]
	v_mfma_f32_16x16x32_bf16 v[32:35], v[144:147], v[198:201], v[32:35]
	v_mfma_f32_16x16x32_bf16 v[28:31], v[158:161], v[198:201], v[28:31]
	v_mfma_f32_16x16x32_bf16 v[16:19], v[144:147], v[210:213], v[16:19]
	v_mfma_f32_16x16x32_bf16 v[12:15], v[158:161], v[210:213], v[12:15]
	v_mfma_f32_16x16x32_bf16 v[64:67], v[154:157], v[186:189], v[64:67]
	v_mfma_f32_16x16x32_bf16 v[60:63], v[162:165], v[186:189], v[60:63]
	v_mfma_f32_16x16x32_bf16 v[48:51], v[154:157], v[194:197], v[48:51]
	v_mfma_f32_16x16x32_bf16 v[44:47], v[162:165], v[194:197], v[44:47]
	v_mfma_f32_16x16x32_bf16 v[32:35], v[154:157], v[202:205], v[32:35]
	v_mfma_f32_16x16x32_bf16 v[28:31], v[162:165], v[202:205], v[28:31]
	v_mfma_f32_16x16x32_bf16 v[16:19], v[154:157], v[218:221], v[16:19]
	v_mfma_f32_16x16x32_bf16 v[12:15], v[162:165], v[218:221], v[12:15]
	v_mfma_f32_16x16x32_bf16 v[56:59], v[166:169], v[182:185], v[56:59]
	v_mfma_f32_16x16x32_bf16 v[52:55], v[174:177], v[182:185], v[52:55]
	v_mfma_f32_16x16x32_bf16 v[40:43], v[166:169], v[190:193], v[40:43]
	v_mfma_f32_16x16x32_bf16 v[36:39], v[174:177], v[190:193], v[36:39]
	v_mfma_f32_16x16x32_bf16 v[24:27], v[166:169], v[198:201], v[24:27]
	v_mfma_f32_16x16x32_bf16 v[20:23], v[174:177], v[198:201], v[20:23]
	v_mfma_f32_16x16x32_bf16 v[8:11], v[166:169], v[210:213], v[8:11]
	v_mfma_f32_16x16x32_bf16 v[4:7], v[174:177], v[210:213], v[4:7]
	v_mfma_f32_16x16x32_bf16 v[56:59], v[170:173], v[186:189], v[56:59]
	v_mfma_f32_16x16x32_bf16 v[52:55], v[178:181], v[186:189], v[52:55]
	v_mfma_f32_16x16x32_bf16 v[40:43], v[170:173], v[194:197], v[40:43]
	v_mfma_f32_16x16x32_bf16 v[36:39], v[178:181], v[194:197], v[36:39]
	v_mfma_f32_16x16x32_bf16 v[24:27], v[170:173], v[202:205], v[24:27]
	v_mfma_f32_16x16x32_bf16 v[20:23], v[178:181], v[202:205], v[20:23]
	v_mfma_f32_16x16x32_bf16 v[8:11], v[170:173], v[218:221], v[8:11]
	v_mfma_f32_16x16x32_bf16 v[4:7], v[178:181], v[218:221], v[4:7]
	s_barrier
	v_add_u32_e32 v2, s79, v151
	ds_read_b128 v[144:147], v2
	ds_read_b128 v[154:157], v2 offset:1024
	ds_read_b128 v[158:161], v2 offset:2048
	ds_read_b128 v[162:165], v2 offset:3072
	v_add_u32_e32 v2, s80, v151
	ds_read_b128 v[166:169], v2
	ds_read_b128 v[170:173], v2 offset:1024
	ds_read_b128 v[174:177], v2 offset:2048
	ds_read_b128 v[178:181], v2 offset:3072
	s_add_u32 s28, s28, 0x40000
	s_addc_u32 s29, s29, 0
	s_mov_b32 m0, s37
	v_lshl_add_u64 v[226:227], s[28:29], 0, v[138:139]
	ds_read_b128 v[182:185], v152 offset:32768
	ds_read_b128 v[186:189], v152 offset:33792
	ds_read_b128 v[190:193], v152 offset:34816
	ds_read_b128 v[194:197], v152 offset:35840
	ds_read_b128 v[198:201], v152 offset:36864
	ds_read_b128 v[202:205], v152 offset:37888
	ds_read_b128 v[210:213], v152 offset:38912
	ds_read_b128 v[218:221], v152 offset:39936
	global_load_lds_dwordx4 v[226:227], off
	v_lshl_add_u64 v[226:227], s[28:29], 0, v[134:135]
	s_mov_b32 m0, s38
	s_nop 0
	global_load_lds_dwordx4 v[226:227], off
	s_waitcnt vmcnt(8)
	s_waitcnt lgkmcnt(0)
	s_barrier
	s_waitcnt lgkmcnt(0)
	v_mfma_f32_16x16x32_bf16 v[128:131], v[144:147], v[182:185], v[128:131]
	v_mfma_f32_16x16x32_bf16 v[124:127], v[158:161], v[182:185], v[124:127]
	v_mfma_f32_16x16x32_bf16 v[112:115], v[144:147], v[190:193], v[112:115]
	v_mfma_f32_16x16x32_bf16 v[108:111], v[158:161], v[190:193], v[108:111]
	v_mfma_f32_16x16x32_bf16 v[96:99], v[144:147], v[198:201], v[96:99]
	v_mfma_f32_16x16x32_bf16 v[92:95], v[158:161], v[198:201], v[92:95]
	v_mfma_f32_16x16x32_bf16 v[80:83], v[144:147], v[210:213], v[80:83]
	v_mfma_f32_16x16x32_bf16 v[76:79], v[158:161], v[210:213], v[76:79]
	v_mfma_f32_16x16x32_bf16 v[128:131], v[154:157], v[186:189], v[128:131]
	v_mfma_f32_16x16x32_bf16 v[124:127], v[162:165], v[186:189], v[124:127]
	v_mfma_f32_16x16x32_bf16 v[112:115], v[154:157], v[194:197], v[112:115]
	v_mfma_f32_16x16x32_bf16 v[108:111], v[162:165], v[194:197], v[108:111]
	v_mfma_f32_16x16x32_bf16 v[96:99], v[154:157], v[202:205], v[96:99]
	v_mfma_f32_16x16x32_bf16 v[92:95], v[162:165], v[202:205], v[92:95]
	v_mfma_f32_16x16x32_bf16 v[80:83], v[154:157], v[218:221], v[80:83]
	v_mfma_f32_16x16x32_bf16 v[76:79], v[162:165], v[218:221], v[76:79]
	v_mfma_f32_16x16x32_bf16 v[120:123], v[166:169], v[182:185], v[120:123]
	v_mfma_f32_16x16x32_bf16 v[116:119], v[174:177], v[182:185], v[116:119]
	v_mfma_f32_16x16x32_bf16 v[104:107], v[166:169], v[190:193], v[104:107]
	v_mfma_f32_16x16x32_bf16 v[100:103], v[174:177], v[190:193], v[100:103]
	v_mfma_f32_16x16x32_bf16 v[88:91], v[166:169], v[198:201], v[88:91]
	v_mfma_f32_16x16x32_bf16 v[84:87], v[174:177], v[198:201], v[84:87]
	v_mfma_f32_16x16x32_bf16 v[72:75], v[166:169], v[210:213], v[72:75]
	v_mfma_f32_16x16x32_bf16 v[68:71], v[174:177], v[210:213], v[68:71]
	v_mfma_f32_16x16x32_bf16 v[120:123], v[170:173], v[186:189], v[120:123]
	v_mfma_f32_16x16x32_bf16 v[116:119], v[178:181], v[186:189], v[116:119]
	v_mfma_f32_16x16x32_bf16 v[104:107], v[170:173], v[194:197], v[104:107]
	v_mfma_f32_16x16x32_bf16 v[100:103], v[178:181], v[194:197], v[100:103]
	v_mfma_f32_16x16x32_bf16 v[88:91], v[170:173], v[202:205], v[88:91]
	v_mfma_f32_16x16x32_bf16 v[84:87], v[178:181], v[202:205], v[84:87]
	v_mfma_f32_16x16x32_bf16 v[72:75], v[170:173], v[218:221], v[72:75]
	v_mfma_f32_16x16x32_bf16 v[68:71], v[178:181], v[218:221], v[68:71]
	s_barrier
	s_add_i32 s28, s79, s35
	v_lshl_add_u64 v[148:149], v[148:149], 0, s[56:57]
	s_mov_b32 m0, s28
	ds_read_b128 v[182:185], v152 offset:49152
	ds_read_b128 v[186:189], v152 offset:50176
	ds_read_b128 v[190:193], v152 offset:51200
	ds_read_b128 v[194:197], v152 offset:52224
	ds_read_b128 v[198:201], v152 offset:53248
	ds_read_b128 v[202:205], v152 offset:54272
	ds_read_b128 v[210:213], v152 offset:55296
	ds_read_b128 v[218:221], v152 offset:56320
	global_load_lds_dwordx4 v[148:149], off
	s_add_i32 m0, s28, 0x2000
	s_add_u32 s26, s26, 0x40080
	v_lshl_add_u64 v[148:149], v[206:207], 0, s[56:57]
	s_addc_u32 s27, s27, 0
	s_add_i32 s28, s80, s35
	global_load_lds_dwordx4 v[148:149], off
	v_lshl_add_u64 v[148:149], s[26:27], 0, v[136:137]
	s_mov_b32 m0, s28
	s_nop 0
	global_load_lds_dwordx4 v[148:149], off
	v_lshl_add_u64 v[148:149], s[26:27], 0, v[132:133]
	s_add_i32 m0, s28, 0x2000
	s_nop 0
	global_load_lds_dwordx4 v[148:149], off
	v_lshl_add_u64 v[148:149], v[222:223], 0, s[56:57]
	s_mov_b32 m0, s41
	s_nop 0
	global_load_lds_dwordx4 v[148:149], off
	v_lshl_add_u64 v[148:149], v[224:225], 0, s[56:57]
	s_mov_b32 m0, s42
	s_nop 0
	global_load_lds_dwordx4 v[148:149], off
	s_waitcnt vmcnt(8)
	s_waitcnt lgkmcnt(0)
	s_barrier
	s_waitcnt lgkmcnt(0)
	v_mfma_f32_16x16x32_bf16 v[64:67], v[144:147], v[182:185], v[64:67]
	v_mfma_f32_16x16x32_bf16 v[60:63], v[158:161], v[182:185], v[60:63]
	v_mfma_f32_16x16x32_bf16 v[48:51], v[144:147], v[190:193], v[48:51]
	v_mfma_f32_16x16x32_bf16 v[44:47], v[158:161], v[190:193], v[44:47]
	v_mfma_f32_16x16x32_bf16 v[32:35], v[144:147], v[198:201], v[32:35]
	v_mfma_f32_16x16x32_bf16 v[28:31], v[158:161], v[198:201], v[28:31]
	v_mfma_f32_16x16x32_bf16 v[16:19], v[144:147], v[210:213], v[16:19]
	v_mfma_f32_16x16x32_bf16 v[12:15], v[158:161], v[210:213], v[12:15]
	v_mfma_f32_16x16x32_bf16 v[64:67], v[154:157], v[186:189], v[64:67]
	v_mfma_f32_16x16x32_bf16 v[60:63], v[162:165], v[186:189], v[60:63]
	v_mfma_f32_16x16x32_bf16 v[48:51], v[154:157], v[194:197], v[48:51]
	v_mfma_f32_16x16x32_bf16 v[44:47], v[162:165], v[194:197], v[44:47]
	v_mfma_f32_16x16x32_bf16 v[32:35], v[154:157], v[202:205], v[32:35]
	v_mfma_f32_16x16x32_bf16 v[28:31], v[162:165], v[202:205], v[28:31]
	v_mfma_f32_16x16x32_bf16 v[16:19], v[154:157], v[218:221], v[16:19]
	v_mfma_f32_16x16x32_bf16 v[12:15], v[162:165], v[218:221], v[12:15]
	v_mfma_f32_16x16x32_bf16 v[56:59], v[166:169], v[182:185], v[56:59]
	v_mfma_f32_16x16x32_bf16 v[52:55], v[174:177], v[182:185], v[52:55]
	v_mfma_f32_16x16x32_bf16 v[40:43], v[166:169], v[190:193], v[40:43]
	v_mfma_f32_16x16x32_bf16 v[36:39], v[174:177], v[190:193], v[36:39]
	v_mfma_f32_16x16x32_bf16 v[24:27], v[166:169], v[198:201], v[24:27]
	v_mfma_f32_16x16x32_bf16 v[20:23], v[174:177], v[198:201], v[20:23]
	v_mfma_f32_16x16x32_bf16 v[8:11], v[166:169], v[210:213], v[8:11]
	v_mfma_f32_16x16x32_bf16 v[4:7], v[174:177], v[210:213], v[4:7]
	v_mfma_f32_16x16x32_bf16 v[56:59], v[170:173], v[186:189], v[56:59]
	v_mfma_f32_16x16x32_bf16 v[52:55], v[178:181], v[186:189], v[52:55]
	v_mfma_f32_16x16x32_bf16 v[40:43], v[170:173], v[194:197], v[40:43]
	v_mfma_f32_16x16x32_bf16 v[36:39], v[178:181], v[194:197], v[36:39]
	v_mfma_f32_16x16x32_bf16 v[24:27], v[170:173], v[202:205], v[24:27]
	v_mfma_f32_16x16x32_bf16 v[20:23], v[178:181], v[202:205], v[20:23]
	v_mfma_f32_16x16x32_bf16 v[8:11], v[170:173], v[218:221], v[8:11]
	v_mfma_f32_16x16x32_bf16 v[4:7], v[178:181], v[218:221], v[4:7]
	s_barrier
	s_add_i32 s53, s53, 2
	s_add_u32 s4, s4, 0x100
	s_addc_u32 s5, s5, 0
	s_add_u32 s51, s51, 0x100
	s_addc_u32 s52, s52, 0
	s_cmp_gt_u32 s53, 13
	s_cbranch_scc0 .LBB0_2540
	s_and_b64 vcc, exec, s[16:17]
	s_cbranch_vccz .LBB0_2543
	s_barrier

.LBB0_2645:
	v_add_u32_e32 v148, s61, v150
	ds_read_b128 v[144:147], v148
	ds_read_b128 v[152:155], v148 offset:1024
	ds_read_b128 v[156:159], v148 offset:2048
	ds_read_b128 v[160:163], v148 offset:3072
	v_add_u32_e32 v148, s77, v150
	ds_read_b128 v[164:167], v148
	ds_read_b128 v[168:171], v148 offset:1024
	ds_read_b128 v[172:175], v148 offset:2048
	ds_read_b128 v[176:179], v148 offset:3072
	s_add_u32 s6, s4, 0xfff00080
	s_addc_u32 s7, s5, -1
	s_cmp_eq_u32 s51, 60
	s_cselect_b32 s9, s29, s7
	s_cselect_b32 s8, s49, s6
	s_cselect_b32 s7, s19, s50
	s_cselect_b32 s6, s18, s27
	v_lshl_add_u64 v[148:149], s[4:5], 0, v[140:141]
	s_add_i32 m0, s17, 0xc000
	ds_read_b128 v[180:183], v151
	ds_read_b128 v[184:187], v151 offset:1024
	ds_read_b128 v[188:191], v151 offset:2048
	ds_read_b128 v[192:195], v151 offset:3072
	ds_read_b128 v[196:199], v151 offset:4096
	ds_read_b128 v[200:203], v151 offset:5120
	ds_read_b128 v[204:207], v151 offset:6144
	ds_read_b128 v[210:213], v151 offset:7168
	global_load_lds_dwordx4 v[148:149], off
	v_lshl_add_u64 v[148:149], s[4:5], 0, v[142:143]
	s_add_i32 m0, s17, 0xe000
	s_nop 0
	global_load_lds_dwordx4 v[148:149], off
	s_waitcnt vmcnt(8)
	s_waitcnt lgkmcnt(0)
	s_barrier
	s_waitcnt lgkmcnt(0)
	v_mfma_f32_16x16x32_bf16 v[128:131], v[144:147], v[180:183], v[128:131]
	v_mfma_f32_16x16x32_bf16 v[124:127], v[156:159], v[180:183], v[124:127]
	v_mfma_f32_16x16x32_bf16 v[112:115], v[144:147], v[188:191], v[112:115]
	v_mfma_f32_16x16x32_bf16 v[108:111], v[156:159], v[188:191], v[108:111]
	v_mfma_f32_16x16x32_bf16 v[96:99], v[144:147], v[196:199], v[96:99]
	v_mfma_f32_16x16x32_bf16 v[92:95], v[156:159], v[196:199], v[92:95]
	v_mfma_f32_16x16x32_bf16 v[80:83], v[144:147], v[204:207], v[80:83]
	v_mfma_f32_16x16x32_bf16 v[76:79], v[156:159], v[204:207], v[76:79]
	v_mfma_f32_16x16x32_bf16 v[128:131], v[152:155], v[184:187], v[128:131]
	v_mfma_f32_16x16x32_bf16 v[124:127], v[160:163], v[184:187], v[124:127]
	v_mfma_f32_16x16x32_bf16 v[112:115], v[152:155], v[192:195], v[112:115]
	v_mfma_f32_16x16x32_bf16 v[108:111], v[160:163], v[192:195], v[108:111]
	v_mfma_f32_16x16x32_bf16 v[96:99], v[152:155], v[200:203], v[96:99]
	v_mfma_f32_16x16x32_bf16 v[92:95], v[160:163], v[200:203], v[92:95]
	v_mfma_f32_16x16x32_bf16 v[80:83], v[152:155], v[210:213], v[80:83]
	v_mfma_f32_16x16x32_bf16 v[76:79], v[160:163], v[210:213], v[76:79]
	v_mfma_f32_16x16x32_bf16 v[120:123], v[164:167], v[180:183], v[120:123]
	v_mfma_f32_16x16x32_bf16 v[116:119], v[172:175], v[180:183], v[116:119]
	v_mfma_f32_16x16x32_bf16 v[104:107], v[164:167], v[188:191], v[104:107]
	v_mfma_f32_16x16x32_bf16 v[100:103], v[172:175], v[188:191], v[100:103]
	v_mfma_f32_16x16x32_bf16 v[88:91], v[164:167], v[196:199], v[88:91]
	v_mfma_f32_16x16x32_bf16 v[84:87], v[172:175], v[196:199], v[84:87]
	v_mfma_f32_16x16x32_bf16 v[72:75], v[164:167], v[204:207], v[72:75]
	v_mfma_f32_16x16x32_bf16 v[68:71], v[172:175], v[204:207], v[68:71]
	v_mfma_f32_16x16x32_bf16 v[120:123], v[168:171], v[184:187], v[120:123]
	v_mfma_f32_16x16x32_bf16 v[116:119], v[176:179], v[184:187], v[116:119]
	v_mfma_f32_16x16x32_bf16 v[104:107], v[168:171], v[192:195], v[104:107]
	v_mfma_f32_16x16x32_bf16 v[100:103], v[176:179], v[192:195], v[100:103]
	v_mfma_f32_16x16x32_bf16 v[88:91], v[168:171], v[200:203], v[88:91]
	v_mfma_f32_16x16x32_bf16 v[84:87], v[176:179], v[200:203], v[84:87]
	v_mfma_f32_16x16x32_bf16 v[72:75], v[168:171], v[210:213], v[72:75]
	v_mfma_f32_16x16x32_bf16 v[68:71], v[176:179], v[210:213], v[68:71]
	s_barrier
	s_add_i32 s52, s61, s37
	v_lshl_add_u64 v[148:149], s[6:7], 0, v[136:137]
	s_mov_b32 m0, s52
	ds_read_b128 v[180:183], v151 offset:16384
	ds_read_b128 v[184:187], v151 offset:17408
	ds_read_b128 v[188:191], v151 offset:18432
	ds_read_b128 v[192:195], v151 offset:19456
	ds_read_b128 v[196:199], v151 offset:20480
	ds_read_b128 v[200:203], v151 offset:21504
	ds_read_b128 v[204:207], v151 offset:22528
	ds_read_b128 v[210:213], v151 offset:23552
	global_load_lds_dwordx4 v[148:149], off
	s_add_i32 m0, s52, 0x2000
	s_add_u32 s52, s6, 0x100000
	v_lshl_add_u64 v[218:219], s[6:7], 0, v[132:133]
	s_addc_u32 s53, s7, 0
	s_add_i32 s58, s77, s37
	global_load_lds_dwordx4 v[218:219], off
	v_lshl_add_u64 v[220:221], s[52:53], 0, v[136:137]
	s_mov_b32 m0, s58
	v_lshl_add_u64 v[222:223], s[8:9], 0, v[134:135]
	global_load_lds_dwordx4 v[220:221], off
	v_lshl_add_u64 v[220:221], s[52:53], 0, v[132:133]
	s_add_i32 m0, s58, 0x2000
	s_nop 0
	global_load_lds_dwordx4 v[220:221], off
	v_lshl_add_u64 v[220:221], s[8:9], 0, v[138:139]
	s_mov_b32 m0, s17
	s_nop 0
	global_load_lds_dwordx4 v[220:221], off
	s_mov_b32 m0, s39
	s_nop 0
	global_load_lds_dwordx4 v[222:223], off
	s_waitcnt vmcnt(8)
	s_waitcnt lgkmcnt(0)
	s_barrier
	s_waitcnt lgkmcnt(0)
	v_mfma_f32_16x16x32_bf16 v[64:67], v[144:147], v[180:183], v[64:67]
	v_mfma_f32_16x16x32_bf16 v[60:63], v[156:159], v[180:183], v[60:63]
	v_mfma_f32_16x16x32_bf16 v[48:51], v[144:147], v[188:191], v[48:51]
	v_mfma_f32_16x16x32_bf16 v[44:47], v[156:159], v[188:191], v[44:47]
	v_mfma_f32_16x16x32_bf16 v[32:35], v[144:147], v[196:199], v[32:35]
	v_mfma_f32_16x16x32_bf16 v[28:31], v[156:159], v[196:199], v[28:31]
	v_mfma_f32_16x16x32_bf16 v[16:19], v[144:147], v[204:207], v[16:19]
	v_mfma_f32_16x16x32_bf16 v[12:15], v[156:159], v[204:207], v[12:15]
	v_mfma_f32_16x16x32_bf16 v[64:67], v[152:155], v[184:187], v[64:67]
	v_mfma_f32_16x16x32_bf16 v[60:63], v[160:163], v[184:187], v[60:63]
	v_mfma_f32_16x16x32_bf16 v[48:51], v[152:155], v[192:195], v[48:51]
	v_mfma_f32_16x16x32_bf16 v[44:47], v[160:163], v[192:195], v[44:47]
	v_mfma_f32_16x16x32_bf16 v[32:35], v[152:155], v[200:203], v[32:35]
	v_mfma_f32_16x16x32_bf16 v[28:31], v[160:163], v[200:203], v[28:31]
	v_mfma_f32_16x16x32_bf16 v[16:19], v[152:155], v[210:213], v[16:19]
	v_mfma_f32_16x16x32_bf16 v[12:15], v[160:163], v[210:213], v[12:15]
	v_mfma_f32_16x16x32_bf16 v[56:59], v[164:167], v[180:183], v[56:59]
	v_mfma_f32_16x16x32_bf16 v[52:55], v[172:175], v[180:183], v[52:55]
	v_mfma_f32_16x16x32_bf16 v[40:43], v[164:167], v[188:191], v[40:43]
	v_mfma_f32_16x16x32_bf16 v[36:39], v[172:175], v[188:191], v[36:39]
	v_mfma_f32_16x16x32_bf16 v[24:27], v[164:167], v[196:199], v[24:27]
	v_mfma_f32_16x16x32_bf16 v[20:23], v[172:175], v[196:199], v[20:23]
	v_mfma_f32_16x16x32_bf16 v[8:11], v[164:167], v[204:207], v[8:11]
	v_mfma_f32_16x16x32_bf16 v[4:7], v[172:175], v[204:207], v[4:7]
	v_mfma_f32_16x16x32_bf16 v[56:59], v[168:171], v[184:187], v[56:59]
	v_mfma_f32_16x16x32_bf16 v[52:55], v[176:179], v[184:187], v[52:55]
	v_mfma_f32_16x16x32_bf16 v[40:43], v[168:171], v[192:195], v[40:43]
	v_mfma_f32_16x16x32_bf16 v[36:39], v[176:179], v[192:195], v[36:39]
	v_mfma_f32_16x16x32_bf16 v[24:27], v[168:171], v[200:203], v[24:27]
	v_mfma_f32_16x16x32_bf16 v[20:23], v[176:179], v[200:203], v[20:23]
	v_mfma_f32_16x16x32_bf16 v[8:11], v[168:171], v[210:213], v[8:11]
	v_mfma_f32_16x16x32_bf16 v[4:7], v[176:179], v[210:213], v[4:7]
	s_barrier
	v_add_u32_e32 v160, s79, v150
	v_add_u32_e32 v176, s80, v150
	ds_read_b128 v[144:147], v160
	ds_read_b128 v[152:155], v160 offset:1024
	ds_read_b128 v[156:159], v160 offset:2048
	ds_read_b128 v[160:163], v160 offset:3072
	ds_read_b128 v[164:167], v176
	ds_read_b128 v[168:171], v176 offset:1024
	ds_read_b128 v[172:175], v176 offset:2048
	ds_read_b128 v[176:179], v176 offset:3072
	s_add_u32 s8, s8, 0x100000
	s_addc_u32 s9, s9, 0
	s_mov_b32 m0, s40
	v_lshl_add_u64 v[224:225], s[8:9], 0, v[138:139]
	ds_read_b128 v[180:183], v151 offset:32768
	ds_read_b128 v[184:187], v151 offset:33792
	ds_read_b128 v[188:191], v151 offset:34816
	ds_read_b128 v[192:195], v151 offset:35840
	ds_read_b128 v[196:199], v151 offset:36864
	ds_read_b128 v[200:203], v151 offset:37888
	ds_read_b128 v[204:207], v151 offset:38912
	ds_read_b128 v[210:213], v151 offset:39936
	global_load_lds_dwordx4 v[224:225], off
	v_lshl_add_u64 v[224:225], s[8:9], 0, v[134:135]
	s_mov_b32 m0, s41
	s_nop 0
	global_load_lds_dwordx4 v[224:225], off
	s_waitcnt vmcnt(8)
	s_waitcnt lgkmcnt(0)
	s_barrier
	s_waitcnt lgkmcnt(0)
	v_mfma_f32_16x16x32_bf16 v[128:131], v[144:147], v[180:183], v[128:131]
	v_mfma_f32_16x16x32_bf16 v[124:127], v[156:159], v[180:183], v[124:127]
	v_mfma_f32_16x16x32_bf16 v[112:115], v[144:147], v[188:191], v[112:115]
	v_mfma_f32_16x16x32_bf16 v[108:111], v[156:159], v[188:191], v[108:111]
	v_mfma_f32_16x16x32_bf16 v[96:99], v[144:147], v[196:199], v[96:99]
	v_mfma_f32_16x16x32_bf16 v[92:95], v[156:159], v[196:199], v[92:95]
	v_mfma_f32_16x16x32_bf16 v[80:83], v[144:147], v[204:207], v[80:83]
	v_mfma_f32_16x16x32_bf16 v[76:79], v[156:159], v[204:207], v[76:79]
	v_mfma_f32_16x16x32_bf16 v[128:131], v[152:155], v[184:187], v[128:131]
	v_mfma_f32_16x16x32_bf16 v[124:127], v[160:163], v[184:187], v[124:127]
	v_mfma_f32_16x16x32_bf16 v[112:115], v[152:155], v[192:195], v[112:115]
	v_mfma_f32_16x16x32_bf16 v[108:111], v[160:163], v[192:195], v[108:111]
	v_mfma_f32_16x16x32_bf16 v[96:99], v[152:155], v[200:203], v[96:99]
	v_mfma_f32_16x16x32_bf16 v[92:95], v[160:163], v[200:203], v[92:95]
	v_mfma_f32_16x16x32_bf16 v[80:83], v[152:155], v[210:213], v[80:83]
	v_mfma_f32_16x16x32_bf16 v[76:79], v[160:163], v[210:213], v[76:79]
	v_mfma_f32_16x16x32_bf16 v[120:123], v[164:167], v[180:183], v[120:123]
	v_mfma_f32_16x16x32_bf16 v[116:119], v[172:175], v[180:183], v[116:119]
	v_mfma_f32_16x16x32_bf16 v[104:107], v[164:167], v[188:191], v[104:107]
	v_mfma_f32_16x16x32_bf16 v[100:103], v[172:175], v[188:191], v[100:103]
	v_mfma_f32_16x16x32_bf16 v[88:91], v[164:167], v[196:199], v[88:91]
	v_mfma_f32_16x16x32_bf16 v[84:87], v[172:175], v[196:199], v[84:87]
	v_mfma_f32_16x16x32_bf16 v[72:75], v[164:167], v[204:207], v[72:75]
	v_mfma_f32_16x16x32_bf16 v[68:71], v[172:175], v[204:207], v[68:71]
	v_mfma_f32_16x16x32_bf16 v[120:123], v[168:171], v[184:187], v[120:123]
	v_mfma_f32_16x16x32_bf16 v[116:119], v[176:179], v[184:187], v[116:119]
	v_mfma_f32_16x16x32_bf16 v[104:107], v[168:171], v[192:195], v[104:107]
	v_mfma_f32_16x16x32_bf16 v[100:103], v[176:179], v[192:195], v[100:103]
	v_mfma_f32_16x16x32_bf16 v[88:91], v[168:171], v[200:203], v[88:91]
	v_mfma_f32_16x16x32_bf16 v[84:87], v[176:179], v[200:203], v[84:87]
	v_mfma_f32_16x16x32_bf16 v[72:75], v[168:171], v[210:213], v[72:75]
	v_mfma_f32_16x16x32_bf16 v[68:71], v[176:179], v[210:213], v[68:71]
	s_barrier
	s_add_i32 s8, s79, s37
	v_lshl_add_u64 v[148:149], v[148:149], 0, s[56:57]
	s_mov_b32 m0, s8
	ds_read_b128 v[180:183], v151 offset:49152
	ds_read_b128 v[184:187], v151 offset:50176
	ds_read_b128 v[188:191], v151 offset:51200
	ds_read_b128 v[192:195], v151 offset:52224
	ds_read_b128 v[196:199], v151 offset:53248
	ds_read_b128 v[200:203], v151 offset:54272
	ds_read_b128 v[204:207], v151 offset:55296
	ds_read_b128 v[210:213], v151 offset:56320
	global_load_lds_dwordx4 v[148:149], off
	s_add_i32 m0, s8, 0x2000
	s_add_u32 s6, s6, 0x100080
	v_lshl_add_u64 v[148:149], v[218:219], 0, s[56:57]
	s_addc_u32 s7, s7, 0
	s_add_i32 s8, s80, s37
	global_load_lds_dwordx4 v[148:149], off
	v_lshl_add_u64 v[148:149], s[6:7], 0, v[136:137]
	s_mov_b32 m0, s8
	s_nop 0
	global_load_lds_dwordx4 v[148:149], off
	v_lshl_add_u64 v[148:149], s[6:7], 0, v[132:133]
	s_add_i32 m0, s8, 0x2000
	s_nop 0
	global_load_lds_dwordx4 v[148:149], off
	v_lshl_add_u64 v[148:149], v[220:221], 0, s[56:57]
	s_mov_b32 m0, s43
	s_nop 0
	global_load_lds_dwordx4 v[148:149], off
	v_lshl_add_u64 v[148:149], v[222:223], 0, s[56:57]
	s_mov_b32 m0, s44
	s_nop 0
	global_load_lds_dwordx4 v[148:149], off
	s_waitcnt vmcnt(8)
	s_waitcnt lgkmcnt(0)
	s_barrier
	s_waitcnt lgkmcnt(0)
	v_mfma_f32_16x16x32_bf16 v[64:67], v[144:147], v[180:183], v[64:67]
	v_mfma_f32_16x16x32_bf16 v[60:63], v[156:159], v[180:183], v[60:63]
	v_mfma_f32_16x16x32_bf16 v[48:51], v[144:147], v[188:191], v[48:51]
	v_mfma_f32_16x16x32_bf16 v[44:47], v[156:159], v[188:191], v[44:47]
	v_mfma_f32_16x16x32_bf16 v[32:35], v[144:147], v[196:199], v[32:35]
	v_mfma_f32_16x16x32_bf16 v[28:31], v[156:159], v[196:199], v[28:31]
	v_mfma_f32_16x16x32_bf16 v[16:19], v[144:147], v[204:207], v[16:19]
	v_mfma_f32_16x16x32_bf16 v[12:15], v[156:159], v[204:207], v[12:15]
	v_mfma_f32_16x16x32_bf16 v[64:67], v[152:155], v[184:187], v[64:67]
	v_mfma_f32_16x16x32_bf16 v[60:63], v[160:163], v[184:187], v[60:63]
	v_mfma_f32_16x16x32_bf16 v[48:51], v[152:155], v[192:195], v[48:51]
	v_mfma_f32_16x16x32_bf16 v[44:47], v[160:163], v[192:195], v[44:47]
	v_mfma_f32_16x16x32_bf16 v[32:35], v[152:155], v[200:203], v[32:35]
	v_mfma_f32_16x16x32_bf16 v[28:31], v[160:163], v[200:203], v[28:31]
	v_mfma_f32_16x16x32_bf16 v[16:19], v[152:155], v[210:213], v[16:19]
	v_mfma_f32_16x16x32_bf16 v[12:15], v[160:163], v[210:213], v[12:15]
	v_mfma_f32_16x16x32_bf16 v[56:59], v[164:167], v[180:183], v[56:59]
	v_mfma_f32_16x16x32_bf16 v[52:55], v[172:175], v[180:183], v[52:55]
	v_mfma_f32_16x16x32_bf16 v[40:43], v[164:167], v[188:191], v[40:43]
	v_mfma_f32_16x16x32_bf16 v[36:39], v[172:175], v[188:191], v[36:39]
	v_mfma_f32_16x16x32_bf16 v[24:27], v[164:167], v[196:199], v[24:27]
	v_mfma_f32_16x16x32_bf16 v[20:23], v[172:175], v[196:199], v[20:23]
	v_mfma_f32_16x16x32_bf16 v[8:11], v[164:167], v[204:207], v[8:11]
	v_mfma_f32_16x16x32_bf16 v[4:7], v[172:175], v[204:207], v[4:7]
	v_mfma_f32_16x16x32_bf16 v[56:59], v[168:171], v[184:187], v[56:59]
	v_mfma_f32_16x16x32_bf16 v[52:55], v[176:179], v[184:187], v[52:55]
	v_mfma_f32_16x16x32_bf16 v[40:43], v[168:171], v[192:195], v[40:43]
	v_mfma_f32_16x16x32_bf16 v[36:39], v[176:179], v[192:195], v[36:39]
	v_mfma_f32_16x16x32_bf16 v[24:27], v[168:171], v[200:203], v[24:27]
	v_mfma_f32_16x16x32_bf16 v[20:23], v[176:179], v[200:203], v[20:23]
	v_mfma_f32_16x16x32_bf16 v[8:11], v[168:171], v[210:213], v[8:11]
	v_mfma_f32_16x16x32_bf16 v[4:7], v[176:179], v[210:213], v[4:7]
	s_barrier
	s_add_i32 s51, s51, 2
	s_add_u32 s4, s4, 0x100
	s_addc_u32 s5, s5, 0
	s_add_u32 s27, s27, 0x100
	s_addc_u32 s50, s50, 0
	s_cmp_gt_u32 s51, 61
	s_cbranch_scc0 .LBB0_2645
	s_and_b64 vcc, exec, s[24:25]
	s_cbranch_vccz .LBB0_2648
	s_barrier
